# all 64 per-segment s_setprio flips in the four GEMM K-loops removed (no priority changes); on top of v95
# speedup vs baseline: 1.0020x; 1.0007x over previous
; #define PG8_STAGE(bufoff, gbase, voff) do { _Pragma("unroll") for (int _i = 0; _i < 2; ++_i) \
;         __builtin_amdgcn_global_load_lds((const unsigned*)((const char*)(gbase) + (voff)[_i]), (PG8_LAS unsigned*)(lds + (bufoff) + ldsw + _i * 8192), 16, 0, 0); } while (0)
; #define PG8_LDA(dst, b, h) do { _Pragma("unroll") for (int m = 0; m < 4; ++m) _Pragma("unroll") for (int k = 0; k < 2; ++k) dst[m][k] = *(const PG8_LAS bf16x8*)(lds + PG8_SA(b, h) + aoff + m * 2048 + k * 1024); } while (0)
; #define PG8_LDB(dst, b, h) do { _Pragma("unroll") for (int n = 0; n < 2; ++n) _Pragma("unroll") for (int k = 0; k < 2; ++k) dst[n][k] = *(const PG8_LAS bf16x8*)(lds + PG8_SB(b, h) + boff + n * 2048 + k * 1024); } while (0)
; #define PG8_WAIT_V(n) asm volatile("s_waitcnt vmcnt(" #n ")" ::: "memory")
; #define PG8_WAIT_L(n) asm volatile("s_waitcnt lgkmcnt(" #n ")" ::: "memory")
; #define PG8_BAR __builtin_amdgcn_s_barrier()
; #define PG8_SCHED __builtin_amdgcn_sched_barrier(0)
;     ...
;             PG8_LDB(B0, 0, 0); PG8_LDB(B1, 0, 1); PG8_SCHED; PG8_LDA(At, 0, 0); PG8_STAGE(PG8_SA(1, 1), a1 + hstep, voffA);
;             PG8_WAIT_V(8); PG8_WAIT_L(0); PG8_BAR; PG8_MMA(0, 0, At, B0); PG8_MMA(0, 1, At, B1); PG8_BAR; PG8_SCHED;
;             PG8_LDA(At, 0, 1); PG8_STAGE(PG8_SB(0, 0), b2, voffB); PG8_STAGE(PG8_SB(0, 1), b2 + hstepB, voffB); PG8_STAGE(PG8_SA(0, 0), a2, voffA);
;             PG8_WAIT_V(8); PG8_WAIT_L(0); PG8_BAR; PG8_MMA(1, 0, At, B0); PG8_MMA(1, 1, At, B1); PG8_BAR; PG8_SCHED;
.Lpka_da:
	s_waitcnt lgkmcnt(0)
	s_barrier
	s_waitcnt lgkmcnt(0)
	v_mfma_f32_16x16x32_bf16 v[132:135], v[144:147], v[210:213], v[132:135]
	v_mfma_f32_16x16x32_bf16 v[128:131], v[152:155], v[210:213], v[128:131]
	v_mfma_f32_16x16x32_bf16 v[116:119], v[144:147], v[218:221], v[116:119]
	v_mfma_f32_16x16x32_bf16 v[112:115], v[152:155], v[218:221], v[112:115]
	v_mfma_f32_16x16x32_bf16 v[100:103], v[144:147], v[226:229], v[100:103]
	v_mfma_f32_16x16x32_bf16 v[96:99], v[152:155], v[226:229], v[96:99]
	v_mfma_f32_16x16x32_bf16 v[84:87], v[144:147], v[234:237], v[84:87]
	v_mfma_f32_16x16x32_bf16 v[80:83], v[152:155], v[234:237], v[80:83]
	v_mfma_f32_16x16x32_bf16 v[132:135], v[148:151], v[214:217], v[132:135]
	v_mfma_f32_16x16x32_bf16 v[128:131], v[156:159], v[214:217], v[128:131]
	v_mfma_f32_16x16x32_bf16 v[116:119], v[148:151], v[222:225], v[116:119]
	v_mfma_f32_16x16x32_bf16 v[112:115], v[156:159], v[222:225], v[112:115]
	v_mfma_f32_16x16x32_bf16 v[100:103], v[148:151], v[230:233], v[100:103]
	v_mfma_f32_16x16x32_bf16 v[96:99], v[156:159], v[230:233], v[96:99]
	v_mfma_f32_16x16x32_bf16 v[84:87], v[148:151], v[238:241], v[84:87]
	v_mfma_f32_16x16x32_bf16 v[80:83], v[156:159], v[238:241], v[80:83]
	v_mfma_f32_16x16x32_bf16 v[140:143], v[186:189], v[210:213], v[140:143]
	v_mfma_f32_16x16x32_bf16 v[136:139], v[202:205], v[210:213], v[136:139]
	v_mfma_f32_16x16x32_bf16 v[124:127], v[186:189], v[218:221], v[124:127]
	v_mfma_f32_16x16x32_bf16 v[120:123], v[202:205], v[218:221], v[120:123]
	v_mfma_f32_16x16x32_bf16 v[108:111], v[186:189], v[226:229], v[108:111]
	v_mfma_f32_16x16x32_bf16 v[104:107], v[202:205], v[226:229], v[104:107]
	v_mfma_f32_16x16x32_bf16 v[92:95], v[186:189], v[234:237], v[92:95]
	v_mfma_f32_16x16x32_bf16 v[88:91], v[202:205], v[234:237], v[88:91]
	v_mfma_f32_16x16x32_bf16 v[140:143], v[198:201], v[214:217], v[140:143]
	v_mfma_f32_16x16x32_bf16 v[136:139], v[206:209], v[214:217], v[136:139]
	v_mfma_f32_16x16x32_bf16 v[124:127], v[198:201], v[222:225], v[124:127]
	v_mfma_f32_16x16x32_bf16 v[120:123], v[206:209], v[222:225], v[120:123]
	v_mfma_f32_16x16x32_bf16 v[108:111], v[198:201], v[230:233], v[108:111]
	v_mfma_f32_16x16x32_bf16 v[104:107], v[206:209], v[230:233], v[104:107]
	v_mfma_f32_16x16x32_bf16 v[92:95], v[198:201], v[238:241], v[92:95]
	v_mfma_f32_16x16x32_bf16 v[88:91], v[206:209], v[238:241], v[88:91]
	s_barrier
	s_add_i32 s82, s82, s15
	s_mov_b32 m0, s82
	ds_read_b128 v[210:213], v197 offset:16384
	ds_read_b128 v[214:217], v197 offset:17408
	ds_read_b128 v[218:221], v197 offset:18432
	ds_read_b128 v[222:225], v197 offset:19456
	ds_read_b128 v[226:229], v197 offset:20480
	ds_read_b128 v[230:233], v197 offset:21504
	ds_read_b128 v[234:237], v197 offset:22528
	ds_read_b128 v[238:241], v197 offset:23552
	global_load_lds_dwordx4 v170, s[72:73]
	s_add_i32 m0, s82, 0x2000
	s_add_u32 s82, s72, 0x10000
	s_addc_u32 s83, s73, 0
	s_add_i32 s86, s86, s15
	global_load_lds_dwordx4 v166, s[72:73]
	s_mov_b32 m0, s86
	s_nop 0
	global_load_lds_dwordx4 v170, s[82:83]
	s_add_i32 m0, s86, 0x2000
	s_nop 0
	global_load_lds_dwordx4 v166, s[82:83]
	s_mov_b32 m0, s63
	s_nop 0
	global_load_lds_dwordx4 v172, s[76:77]
	s_mov_b32 m0, s64
	s_nop 0
	global_load_lds_dwordx4 v168, s[76:77]
	s_lshl_b32 s100, s100, 1
	s_and_b32 s100, s100, 6
	s_bcnt1_i32_b32 vcc_lo, s100
	s_cmp_eq_u32 vcc_lo, 0
	s_cbranch_scc1 .Lpka_w8b
	s_cmp_eq_u32 vcc_lo, 1
	s_cbranch_scc1 .Lpka_w9b
	s_waitcnt vmcnt(10)
	s_branch .Lpka_db

; #define PG8_STAGE(bufoff, gbase, voff) do { _Pragma("unroll") for (int _i = 0; _i < 2; ++_i) \
;         __builtin_amdgcn_global_load_lds((const unsigned*)((const char*)(gbase) + (voff)[_i]), (PG8_LAS unsigned*)(lds + (bufoff) + ldsw + _i * 8192), 16, 0, 0); } while (0)
; #define PG8_LDA(dst, b, h) do { _Pragma("unroll") for (int m = 0; m < 4; ++m) _Pragma("unroll") for (int k = 0; k < 2; ++k) dst[m][k] = *(const PG8_LAS bf16x8*)(lds + PG8_SA(b, h) + aoff + m * 2048 + k * 1024); } while (0)
; #define PG8_LDB(dst, b, h) do { _Pragma("unroll") for (int n = 0; n < 2; ++n) _Pragma("unroll") for (int k = 0; k < 2; ++k) dst[n][k] = *(const PG8_LAS bf16x8*)(lds + PG8_SB(b, h) + boff + n * 2048 + k * 1024); } while (0)
; #define PG8_WAIT_V(n) asm volatile("s_waitcnt vmcnt(" #n ")" ::: "memory")
; #define PG8_WAIT_L(n) asm volatile("s_waitcnt lgkmcnt(" #n ")" ::: "memory")
; #define PG8_BAR __builtin_amdgcn_s_barrier()
; #define PG8_SCHED __builtin_amdgcn_sched_barrier(0)
;     ...
;             PG8_LDA(At, 0, 1); PG8_STAGE(PG8_SB(0, 0), b2, voffB); PG8_STAGE(PG8_SB(0, 1), b2 + hstepB, voffB); PG8_STAGE(PG8_SA(0, 0), a2, voffA);
;             PG8_WAIT_V(8); PG8_WAIT_L(0); PG8_BAR; PG8_MMA(1, 0, At, B0); PG8_MMA(1, 1, At, B1); PG8_BAR; PG8_SCHED;
;             PG8_LDB(B0, 1, 0); PG8_LDB(B1, 1, 1); PG8_SCHED; PG8_LDA(At, 1, 0); PG8_STAGE(PG8_SA(0, 1), a2 + hstep, voffA);
;             PG8_WAIT_V(8); PG8_WAIT_L(0); PG8_BAR; PG8_MMA(0, 0, At, B0); PG8_MMA(0, 1, At, B1); PG8_BAR; PG8_SCHED;
.Lpka_db:
	s_waitcnt lgkmcnt(0)
	s_barrier
	s_waitcnt lgkmcnt(0)
	v_mfma_f32_16x16x32_bf16 v[68:71], v[144:147], v[210:213], v[68:71]
	v_mfma_f32_16x16x32_bf16 v[64:67], v[152:155], v[210:213], v[64:67]
	v_mfma_f32_16x16x32_bf16 v[52:55], v[144:147], v[218:221], v[52:55]
	v_mfma_f32_16x16x32_bf16 v[48:51], v[152:155], v[218:221], v[48:51]
	v_mfma_f32_16x16x32_bf16 v[36:39], v[144:147], v[226:229], v[36:39]
	v_mfma_f32_16x16x32_bf16 v[32:35], v[152:155], v[226:229], v[32:35]
	v_mfma_f32_16x16x32_bf16 v[20:23], v[144:147], v[234:237], v[20:23]
	v_mfma_f32_16x16x32_bf16 v[16:19], v[152:155], v[234:237], v[16:19]
	v_mfma_f32_16x16x32_bf16 v[68:71], v[148:151], v[214:217], v[68:71]
	v_mfma_f32_16x16x32_bf16 v[64:67], v[156:159], v[214:217], v[64:67]
	v_mfma_f32_16x16x32_bf16 v[52:55], v[148:151], v[222:225], v[52:55]
	v_mfma_f32_16x16x32_bf16 v[48:51], v[156:159], v[222:225], v[48:51]
	v_mfma_f32_16x16x32_bf16 v[36:39], v[148:151], v[230:233], v[36:39]
	v_mfma_f32_16x16x32_bf16 v[32:35], v[156:159], v[230:233], v[32:35]
	v_mfma_f32_16x16x32_bf16 v[20:23], v[148:151], v[238:241], v[20:23]
	v_mfma_f32_16x16x32_bf16 v[16:19], v[156:159], v[238:241], v[16:19]
	v_mfma_f32_16x16x32_bf16 v[76:79], v[186:189], v[210:213], v[76:79]
	v_mfma_f32_16x16x32_bf16 v[72:75], v[202:205], v[210:213], v[72:75]
	v_mfma_f32_16x16x32_bf16 v[60:63], v[186:189], v[218:221], v[60:63]
	v_mfma_f32_16x16x32_bf16 v[56:59], v[202:205], v[218:221], v[56:59]
	v_mfma_f32_16x16x32_bf16 v[44:47], v[186:189], v[226:229], v[44:47]
	v_mfma_f32_16x16x32_bf16 v[40:43], v[202:205], v[226:229], v[40:43]
	v_mfma_f32_16x16x32_bf16 v[24:27], v[186:189], v[234:237], v[24:27]
	v_mfma_f32_16x16x32_bf16 v[28:31], v[202:205], v[234:237], v[28:31]
	v_mfma_f32_16x16x32_bf16 v[76:79], v[198:201], v[214:217], v[76:79]
	v_mfma_f32_16x16x32_bf16 v[72:75], v[206:209], v[214:217], v[72:75]
	v_mfma_f32_16x16x32_bf16 v[60:63], v[198:201], v[222:225], v[60:63]
	v_mfma_f32_16x16x32_bf16 v[56:59], v[206:209], v[222:225], v[56:59]
	v_mfma_f32_16x16x32_bf16 v[44:47], v[198:201], v[230:233], v[44:47]
	v_mfma_f32_16x16x32_bf16 v[40:43], v[206:209], v[230:233], v[40:43]
	v_mfma_f32_16x16x32_bf16 v[24:27], v[198:201], v[238:241], v[24:27]
	v_mfma_f32_16x16x32_bf16 v[28:31], v[206:209], v[238:241], v[28:31]
	s_barrier
	s_add_i32 s82, 0, 0x18000
	s_add_i32 s83, 0, 0x1c000
	v_add_u32_e32 v156, s82, v195
	v_add_u32_e32 v183, s83, v195
	ds_read_b128 v[144:147], v156
	ds_read_b128 v[148:151], v156 offset:1024
	ds_read_b128 v[152:155], v156 offset:2048
	ds_read_b128 v[156:159], v156 offset:3072
	ds_read_b128 v[186:189], v183
	ds_read_b128 v[198:201], v183 offset:1024
	ds_read_b128 v[202:205], v183 offset:2048
	ds_read_b128 v[206:209], v183 offset:3072
	s_add_u32 s76, s76, 0x40000
	s_addc_u32 s77, s77, 0
	s_mov_b32 m0, s65
	ds_read_b128 v[210:213], v197 offset:32768
	ds_read_b128 v[214:217], v197 offset:33792
	ds_read_b128 v[218:221], v197 offset:34816
	ds_read_b128 v[222:225], v197 offset:35840
	ds_read_b128 v[226:229], v197 offset:36864
	ds_read_b128 v[230:233], v197 offset:37888
	ds_read_b128 v[234:237], v197 offset:38912
	ds_read_b128 v[238:241], v197 offset:39936
	global_load_lds_dwordx4 v172, s[76:77]
	s_mov_b32 m0, s66
	s_nop 0
	global_load_lds_dwordx4 v168, s[76:77]
	s_lshl_b32 s100, s100, 1
	s_and_b32 s100, s100, 6
	s_cmp_eq_u32 s101, 0
	s_cbranch_scc1 .Lpka_nc
	s_cmp_lt_i32 s81, 2
	s_cbranch_scc1 .Lpka_nc
	s_or_b32 s100, s100, 1
	s_cmp_eq_u32 s101, 8
	s_cbranch_scc1 .Lpka_s0c
	s_cmp_eq_u32 s101, 7
	s_cbranch_scc1 .Lpka_s1c
	s_cmp_eq_u32 s101, 6
	s_cbranch_scc1 .Lpka_s2c
	s_cmp_eq_u32 s101, 5
	s_cbranch_scc1 .Lpka_s3c
	s_cmp_eq_u32 s101, 4
	s_cbranch_scc1 .Lpka_s4c
	s_cmp_eq_u32 s101, 3
	s_cbranch_scc1 .Lpka_s5c
	s_cmp_eq_u32 s101, 2
	s_cbranch_scc1 .Lpka_s6c
	global_store_dwordx4 v[254:255], v[12:15], off offset:64
	s_branch .Lpka_ic

; #define PG8_STAGE(bufoff, gbase, voff) do { _Pragma("unroll") for (int _i = 0; _i < 2; ++_i) \
;         __builtin_amdgcn_global_load_lds((const unsigned*)((const char*)(gbase) + (voff)[_i]), (PG8_LAS unsigned*)(lds + (bufoff) + ldsw + _i * 8192), 16, 0, 0); } while (0)
; #define PG8_LDA(dst, b, h) do { _Pragma("unroll") for (int m = 0; m < 4; ++m) _Pragma("unroll") for (int k = 0; k < 2; ++k) dst[m][k] = *(const PG8_LAS bf16x8*)(lds + PG8_SA(b, h) + aoff + m * 2048 + k * 1024); } while (0)
; #define PG8_LDB(dst, b, h) do { _Pragma("unroll") for (int n = 0; n < 2; ++n) _Pragma("unroll") for (int k = 0; k < 2; ++k) dst[n][k] = *(const PG8_LAS bf16x8*)(lds + PG8_SB(b, h) + boff + n * 2048 + k * 1024); } while (0)
; #define PG8_WAIT_V(n) asm volatile("s_waitcnt vmcnt(" #n ")" ::: "memory")
; #define PG8_WAIT_L(n) asm volatile("s_waitcnt lgkmcnt(" #n ")" ::: "memory")
; #define PG8_BAR __builtin_amdgcn_s_barrier()
; #define PG8_SCHED __builtin_amdgcn_sched_barrier(0)
;     ...
;             PG8_LDB(B0, 1, 0); PG8_LDB(B1, 1, 1); PG8_SCHED; PG8_LDA(At, 1, 0); PG8_STAGE(PG8_SA(0, 1), a2 + hstep, voffA);
;             PG8_WAIT_V(8); PG8_WAIT_L(0); PG8_BAR; PG8_MMA(0, 0, At, B0); PG8_MMA(0, 1, At, B1); PG8_BAR; PG8_SCHED;
;             PG8_LDA(At, 1, 1); PG8_STAGE(PG8_SB(1, 0), b3, voffB); PG8_STAGE(PG8_SB(1, 1), b3 + hstepB, voffB); PG8_STAGE(PG8_SA(1, 0), a3, voffA);
;             PG8_WAIT_V(8); PG8_WAIT_L(0); PG8_BAR; PG8_MMA(1, 0, At, B0); PG8_MMA(1, 1, At, B1); PG8_BAR; PG8_SCHED;
.Lpka_dc:
	s_waitcnt lgkmcnt(0)
	s_barrier
	s_waitcnt lgkmcnt(0)
	v_mfma_f32_16x16x32_bf16 v[132:135], v[144:147], v[210:213], v[132:135]
	v_mfma_f32_16x16x32_bf16 v[128:131], v[152:155], v[210:213], v[128:131]
	v_mfma_f32_16x16x32_bf16 v[116:119], v[144:147], v[218:221], v[116:119]
	v_mfma_f32_16x16x32_bf16 v[112:115], v[152:155], v[218:221], v[112:115]
	v_mfma_f32_16x16x32_bf16 v[100:103], v[144:147], v[226:229], v[100:103]
	v_mfma_f32_16x16x32_bf16 v[96:99], v[152:155], v[226:229], v[96:99]
	v_mfma_f32_16x16x32_bf16 v[84:87], v[144:147], v[234:237], v[84:87]
	v_mfma_f32_16x16x32_bf16 v[80:83], v[152:155], v[234:237], v[80:83]
	v_mfma_f32_16x16x32_bf16 v[132:135], v[148:151], v[214:217], v[132:135]
	v_mfma_f32_16x16x32_bf16 v[128:131], v[156:159], v[214:217], v[128:131]
	v_mfma_f32_16x16x32_bf16 v[116:119], v[148:151], v[222:225], v[116:119]
	v_mfma_f32_16x16x32_bf16 v[112:115], v[156:159], v[222:225], v[112:115]
	v_mfma_f32_16x16x32_bf16 v[100:103], v[148:151], v[230:233], v[100:103]
	v_mfma_f32_16x16x32_bf16 v[96:99], v[156:159], v[230:233], v[96:99]
	v_mfma_f32_16x16x32_bf16 v[84:87], v[148:151], v[238:241], v[84:87]
	v_mfma_f32_16x16x32_bf16 v[80:83], v[156:159], v[238:241], v[80:83]
	v_mfma_f32_16x16x32_bf16 v[140:143], v[186:189], v[210:213], v[140:143]
	v_mfma_f32_16x16x32_bf16 v[136:139], v[202:205], v[210:213], v[136:139]
	v_mfma_f32_16x16x32_bf16 v[124:127], v[186:189], v[218:221], v[124:127]
	v_mfma_f32_16x16x32_bf16 v[120:123], v[202:205], v[218:221], v[120:123]
	v_mfma_f32_16x16x32_bf16 v[108:111], v[186:189], v[226:229], v[108:111]
	v_mfma_f32_16x16x32_bf16 v[104:107], v[202:205], v[226:229], v[104:107]
	v_mfma_f32_16x16x32_bf16 v[92:95], v[186:189], v[234:237], v[92:95]
	v_mfma_f32_16x16x32_bf16 v[88:91], v[202:205], v[234:237], v[88:91]
	v_mfma_f32_16x16x32_bf16 v[140:143], v[198:201], v[214:217], v[140:143]
	v_mfma_f32_16x16x32_bf16 v[136:139], v[206:209], v[214:217], v[136:139]
	v_mfma_f32_16x16x32_bf16 v[124:127], v[198:201], v[222:225], v[124:127]
	v_mfma_f32_16x16x32_bf16 v[120:123], v[206:209], v[222:225], v[120:123]
	v_mfma_f32_16x16x32_bf16 v[108:111], v[198:201], v[230:233], v[108:111]
	v_mfma_f32_16x16x32_bf16 v[104:107], v[206:209], v[230:233], v[104:107]
	v_mfma_f32_16x16x32_bf16 v[92:95], v[198:201], v[238:241], v[92:95]
	v_mfma_f32_16x16x32_bf16 v[88:91], v[206:209], v[238:241], v[88:91]
	s_barrier
	s_add_i32 m0, s82, s15
	s_add_u32 vcc_lo, s72, 0x80
	s_addc_u32 vcc_hi, s73, 0
	ds_read_b128 v[210:213], v197 offset:49152
	ds_read_b128 v[214:217], v197 offset:50176
	ds_read_b128 v[218:221], v197 offset:51200
	ds_read_b128 v[222:225], v197 offset:52224
	ds_read_b128 v[226:229], v197 offset:53248
	ds_read_b128 v[230:233], v197 offset:54272
	ds_read_b128 v[234:237], v197 offset:55296
	ds_read_b128 v[238:241], v197 offset:56320
	global_load_lds_dwordx4 v170, vcc
	s_add_i32 m0, m0, 0x2000
	s_nop 0
	global_load_lds_dwordx4 v166, vcc
	s_add_u32 s72, s72, 0x10080
	s_addc_u32 s73, s73, 0
	s_add_i32 m0, s83, s15
	s_nop 0
	global_load_lds_dwordx4 v170, s[72:73]
	s_add_i32 m0, m0, 0x2000
	s_nop 0
	global_load_lds_dwordx4 v166, s[72:73]
	s_add_u32 vcc_lo, s76, 0xfffc0080
	s_addc_u32 vcc_hi, s77, -1
	s_mov_b32 m0, s74
	s_nop 0
	global_load_lds_dwordx4 v172, vcc
	s_mov_b32 m0, s75
	s_nop 0
	global_load_lds_dwordx4 v168, vcc
	s_lshl_b32 s100, s100, 1
	s_and_b32 s100, s100, 6
	s_bcnt1_i32_b32 vcc_lo, s100
	s_cmp_eq_u32 vcc_lo, 0
	s_cbranch_scc1 .Lpka_w8e
	s_cmp_eq_u32 vcc_lo, 1
	s_cbranch_scc1 .Lpka_w9e
	s_waitcnt vmcnt(10)
	s_branch .Lpka_de

; #define PG8_STAGE(bufoff, gbase, voff) do { _Pragma("unroll") for (int _i = 0; _i < 2; ++_i) \
;         __builtin_amdgcn_global_load_lds((const unsigned*)((const char*)(gbase) + (voff)[_i]), (PG8_LAS unsigned*)(lds + (bufoff) + ldsw + _i * 8192), 16, 0, 0); } while (0)
; #define PG8_LDA(dst, b, h) do { _Pragma("unroll") for (int m = 0; m < 4; ++m) _Pragma("unroll") for (int k = 0; k < 2; ++k) dst[m][k] = *(const PG8_LAS bf16x8*)(lds + PG8_SA(b, h) + aoff + m * 2048 + k * 1024); } while (0)
; #define PG8_LDB(dst, b, h) do { _Pragma("unroll") for (int n = 0; n < 2; ++n) _Pragma("unroll") for (int k = 0; k < 2; ++k) dst[n][k] = *(const PG8_LAS bf16x8*)(lds + PG8_SB(b, h) + boff + n * 2048 + k * 1024); } while (0)
; #define PG8_WAIT_V(n) asm volatile("s_waitcnt vmcnt(" #n ")" ::: "memory")
; #define PG8_WAIT_L(n) asm volatile("s_waitcnt lgkmcnt(" #n ")" ::: "memory")
; #define PG8_BAR __builtin_amdgcn_s_barrier()
;     ...
;         for (int t = 0; t < nt; t += 2) {
;             const bool last = (t == nt - 2);
;             const char* a1 = cA + (size_t)(t + 1) * kstep;
;             const char* a2 = last ? nA : cA + (size_t)(t + 2) * kstep; const char* b2 = last ? nB : cB + (size_t)(t + 2) * kstep;
;             const char* a3 = a2 + kstep; const char* b3 = b2 + kstep;
;             PG8_LDB(B0, 0, 0); PG8_LDB(B1, 0, 1); PG8_SCHED; PG8_LDA(At, 0, 0); PG8_STAGE(PG8_SA(1, 1), a1 + hstep, voffA);
;             PG8_WAIT_V(8); PG8_WAIT_L(0); PG8_BAR; PG8_MMA(0, 0, At, B0); PG8_MMA(0, 1, At, B1); PG8_BAR; PG8_SCHED;
;             PG8_LDA(At, 0, 1); PG8_STAGE(PG8_SB(0, 0), b2, voffB); PG8_STAGE(PG8_SB(0, 1), b2 + hstepB, voffB); PG8_STAGE(PG8_SA(0, 0), a2, voffA);
;             PG8_WAIT_V(8); PG8_WAIT_L(0); PG8_BAR; PG8_MMA(1, 0, At, B0); PG8_MMA(1, 1, At, B1); PG8_BAR; PG8_SCHED;
;             PG8_LDB(B0, 1, 0); PG8_LDB(B1, 1, 1); PG8_SCHED; PG8_LDA(At, 1, 0); PG8_STAGE(PG8_SA(0, 1), a2 + hstep, voffA);
;             PG8_WAIT_V(8); PG8_WAIT_L(0); PG8_BAR; PG8_MMA(0, 0, At, B0); PG8_MMA(0, 1, At, B1); PG8_BAR; PG8_SCHED;
;             PG8_LDA(At, 1, 1); PG8_STAGE(PG8_SB(1, 0), b3, voffB); PG8_STAGE(PG8_SB(1, 1), b3 + hstepB, voffB); PG8_STAGE(PG8_SA(1, 0), a3, voffA);
;             PG8_WAIT_V(8); PG8_WAIT_L(0); PG8_BAR; PG8_MMA(1, 0, At, B0); PG8_MMA(1, 1, At, B1); PG8_BAR; PG8_SCHED;
;         }
;         if constexpr (ALIGN_EPI) { if (wr == 0) PG8_BAR; }
.Lpka_de:
	s_waitcnt lgkmcnt(0)
	s_barrier
	s_waitcnt lgkmcnt(0)
	v_mfma_f32_16x16x32_bf16 v[68:71], v[144:147], v[210:213], v[68:71]
	v_mfma_f32_16x16x32_bf16 v[64:67], v[152:155], v[210:213], v[64:67]
	v_mfma_f32_16x16x32_bf16 v[52:55], v[144:147], v[218:221], v[52:55]
	v_mfma_f32_16x16x32_bf16 v[48:51], v[152:155], v[218:221], v[48:51]
	v_mfma_f32_16x16x32_bf16 v[36:39], v[144:147], v[226:229], v[36:39]
	v_mfma_f32_16x16x32_bf16 v[32:35], v[152:155], v[226:229], v[32:35]
	v_mfma_f32_16x16x32_bf16 v[20:23], v[144:147], v[234:237], v[20:23]
	v_mfma_f32_16x16x32_bf16 v[16:19], v[152:155], v[234:237], v[16:19]
	v_mfma_f32_16x16x32_bf16 v[68:71], v[148:151], v[214:217], v[68:71]
	v_mfma_f32_16x16x32_bf16 v[64:67], v[156:159], v[214:217], v[64:67]
	v_mfma_f32_16x16x32_bf16 v[52:55], v[148:151], v[222:225], v[52:55]
	v_mfma_f32_16x16x32_bf16 v[48:51], v[156:159], v[222:225], v[48:51]
	v_mfma_f32_16x16x32_bf16 v[36:39], v[148:151], v[230:233], v[36:39]
	v_mfma_f32_16x16x32_bf16 v[32:35], v[156:159], v[230:233], v[32:35]
	v_mfma_f32_16x16x32_bf16 v[20:23], v[148:151], v[238:241], v[20:23]
	v_mfma_f32_16x16x32_bf16 v[16:19], v[156:159], v[238:241], v[16:19]
	v_mfma_f32_16x16x32_bf16 v[76:79], v[186:189], v[210:213], v[76:79]
	v_mfma_f32_16x16x32_bf16 v[72:75], v[202:205], v[210:213], v[72:75]
	v_mfma_f32_16x16x32_bf16 v[60:63], v[186:189], v[218:221], v[60:63]
	v_mfma_f32_16x16x32_bf16 v[56:59], v[202:205], v[218:221], v[56:59]
	v_mfma_f32_16x16x32_bf16 v[44:47], v[186:189], v[226:229], v[44:47]
	v_mfma_f32_16x16x32_bf16 v[40:43], v[202:205], v[226:229], v[40:43]
	v_mfma_f32_16x16x32_bf16 v[24:27], v[186:189], v[234:237], v[24:27]
	v_mfma_f32_16x16x32_bf16 v[28:31], v[202:205], v[234:237], v[28:31]
	v_mfma_f32_16x16x32_bf16 v[76:79], v[198:201], v[214:217], v[76:79]
	v_mfma_f32_16x16x32_bf16 v[72:75], v[206:209], v[214:217], v[72:75]
	v_mfma_f32_16x16x32_bf16 v[60:63], v[198:201], v[222:225], v[60:63]
	v_mfma_f32_16x16x32_bf16 v[56:59], v[206:209], v[222:225], v[56:59]
	v_mfma_f32_16x16x32_bf16 v[44:47], v[198:201], v[230:233], v[44:47]
	v_mfma_f32_16x16x32_bf16 v[40:43], v[206:209], v[230:233], v[40:43]
	v_mfma_f32_16x16x32_bf16 v[24:27], v[198:201], v[238:241], v[24:27]
	v_mfma_f32_16x16x32_bf16 v[28:31], v[206:209], v[238:241], v[28:31]
	s_barrier
	s_add_i32 s81, s81, 2
	s_add_u32 s38, s38, 0x100
	s_addc_u32 s39, s39, 0
	s_add_u32 s61, s61, 0x100
	s_addc_u32 s80, s80, 0
	s_cmp_gt_u32 s81, 13
	s_cbranch_scc0 .LBB0_206
	v_mov_b32_e32 v162, 0x500
	v_mov_b32_e32 v163, 0
	v_mov_b32_e32 v164, 0x4ff
	v_mov_b32_e32 v165, 0
	v_mov_b32_e32 v190, 0x358637bd
	v_mov_b32_e32 v191, 1
	v_mov_b32_e32 v192, 0x300
	v_mov_b32_e32 v193, 0x200
	s_and_b64 vcc, exec, s[22:23]
	s_cbranch_vccz .LBB0_209
	s_barrier

; #define PG8_STAGE(bufoff, gbase, voff) do { _Pragma("unroll") for (int _i = 0; _i < 2; ++_i) \
;         __builtin_amdgcn_global_load_lds((const unsigned*)((const char*)(gbase) + (voff)[_i]), (PG8_LAS unsigned*)(lds + (bufoff) + ldsw + _i * 8192), 16, 0, 0); } while (0)
; #define PG8_LDA(dst, b, h) do { _Pragma("unroll") for (int m = 0; m < 4; ++m) _Pragma("unroll") for (int k = 0; k < 2; ++k) dst[m][k] = *(const PG8_LAS bf16x8*)(lds + PG8_SA(b, h) + aoff + m * 2048 + k * 1024); } while (0)
; #define PG8_LDB(dst, b, h) do { _Pragma("unroll") for (int n = 0; n < 2; ++n) _Pragma("unroll") for (int k = 0; k < 2; ++k) dst[n][k] = *(const PG8_LAS bf16x8*)(lds + PG8_SB(b, h) + boff + n * 2048 + k * 1024); } while (0)
; #define PG8_WAIT_V(n) asm volatile("s_waitcnt vmcnt(" #n ")" ::: "memory")
; #define PG8_WAIT_L(n) asm volatile("s_waitcnt lgkmcnt(" #n ")" ::: "memory")
; #define PG8_BAR __builtin_amdgcn_s_barrier()
; #define PG8_SCHED __builtin_amdgcn_sched_barrier(0)
;     ...
;             PG8_LDB(B0, 0, 0); PG8_LDB(B1, 0, 1); PG8_SCHED; PG8_LDA(At, 0, 0); PG8_STAGE(PG8_SA(1, 1), a1 + hstep, voffA);
;             PG8_WAIT_V(8); PG8_WAIT_L(0); PG8_BAR; PG8_MMA(0, 0, At, B0); PG8_MMA(0, 1, At, B1); PG8_BAR; PG8_SCHED;
;             PG8_LDA(At, 0, 1); PG8_STAGE(PG8_SB(0, 0), b2, voffB); PG8_STAGE(PG8_SB(0, 1), b2 + hstepB, voffB); PG8_STAGE(PG8_SA(0, 0), a2, voffA);
;             PG8_WAIT_V(8); PG8_WAIT_L(0); PG8_BAR; PG8_MMA(1, 0, At, B0); PG8_MMA(1, 1, At, B1); PG8_BAR; PG8_SCHED;
;             PG8_LDB(B0, 1, 0); PG8_LDB(B1, 1, 1); PG8_SCHED; PG8_LDA(At, 1, 0); PG8_STAGE(PG8_SA(0, 1), a2 + hstep, voffA);
;             PG8_WAIT_V(8); PG8_WAIT_L(0); PG8_BAR; PG8_MMA(0, 0, At, B0); PG8_MMA(0, 1, At, B1); PG8_BAR; PG8_SCHED;
.LBB0_434:
	v_add_u32_e32 v140, s49, v199
	s_waitcnt lgkmcnt(0)
	v_add_u32_e32 v156, s50, v199
	ds_read_b128 v[128:131], v140
	ds_read_b128 v[132:135], v140 offset:1024
	ds_read_b128 v[136:139], v140 offset:2048
	ds_read_b128 v[140:143], v140 offset:3072
	ds_read_b128 v[144:147], v156
	ds_read_b128 v[148:151], v156 offset:1024
	ds_read_b128 v[152:155], v156 offset:2048
	ds_read_b128 v[156:159], v156 offset:3072
	s_add_u32 s22, s24, 0xfffc0080
	s_addc_u32 s23, s25, -1
	s_cmp_eq_u32 s54, 12
	s_cselect_b32 s27, s2, s23
	s_cselect_b32 s26, s15, s22
	s_cselect_b32 s23, s13, s53
	s_cselect_b32 s22, s21, s52
	v_lshl_add_u64 v[196:197], s[24:25], 0, v[184:185]
	s_add_i32 m0, s29, 0xc000
	ds_read_b128 v[160:163], v201
	ds_read_b128 v[164:167], v201 offset:1024
	ds_read_b128 v[168:171], v201 offset:2048
	ds_read_b128 v[172:175], v201 offset:3072
	ds_read_b128 v[192:195], v201 offset:4096
	ds_read_b128 v[202:205], v201 offset:5120
	ds_read_b128 v[206:209], v201 offset:6144
	ds_read_b128 v[210:213], v201 offset:7168
	global_load_lds_dwordx4 v[196:197], off
	v_lshl_add_u64 v[196:197], s[24:25], 0, v[186:187]
	s_add_i32 m0, s29, 0xe000
	s_nop 0
	global_load_lds_dwordx4 v[196:197], off
	s_waitcnt vmcnt(8)
	s_waitcnt lgkmcnt(0)
	s_barrier
	s_waitcnt lgkmcnt(0)
	v_mfma_f32_16x16x32_bf16 v[112:115], v[128:131], v[160:163], v[112:115]
	v_mfma_f32_16x16x32_bf16 v[116:119], v[136:139], v[160:163], v[116:119]
	v_mfma_f32_16x16x32_bf16 v[108:111], v[128:131], v[168:171], v[108:111]
	v_mfma_f32_16x16x32_bf16 v[104:107], v[136:139], v[168:171], v[104:107]
	v_mfma_f32_16x16x32_bf16 v[92:95], v[128:131], v[192:195], v[92:95]
	v_mfma_f32_16x16x32_bf16 v[88:91], v[136:139], v[192:195], v[88:91]
	v_mfma_f32_16x16x32_bf16 v[76:79], v[128:131], v[206:209], v[76:79]
	v_mfma_f32_16x16x32_bf16 v[72:75], v[136:139], v[206:209], v[72:75]
	v_mfma_f32_16x16x32_bf16 v[112:115], v[132:135], v[164:167], v[112:115]
	v_mfma_f32_16x16x32_bf16 v[116:119], v[140:143], v[164:167], v[116:119]
	v_mfma_f32_16x16x32_bf16 v[108:111], v[132:135], v[172:175], v[108:111]
	v_mfma_f32_16x16x32_bf16 v[104:107], v[140:143], v[172:175], v[104:107]
	v_mfma_f32_16x16x32_bf16 v[92:95], v[132:135], v[202:205], v[92:95]
	v_mfma_f32_16x16x32_bf16 v[88:91], v[140:143], v[202:205], v[88:91]
	v_mfma_f32_16x16x32_bf16 v[76:79], v[132:135], v[210:213], v[76:79]
	v_mfma_f32_16x16x32_bf16 v[72:75], v[140:143], v[210:213], v[72:75]
	v_mfma_f32_16x16x32_bf16 v[120:123], v[144:147], v[160:163], v[120:123]
	v_mfma_f32_16x16x32_bf16 v[124:127], v[152:155], v[160:163], v[124:127]
	v_mfma_f32_16x16x32_bf16 v[100:103], v[144:147], v[168:171], v[100:103]
	v_mfma_f32_16x16x32_bf16 v[96:99], v[152:155], v[168:171], v[96:99]
	v_mfma_f32_16x16x32_bf16 v[84:87], v[144:147], v[192:195], v[84:87]
	v_mfma_f32_16x16x32_bf16 v[80:83], v[152:155], v[192:195], v[80:83]
	v_mfma_f32_16x16x32_bf16 v[68:71], v[144:147], v[206:209], v[68:71]
	v_mfma_f32_16x16x32_bf16 v[64:67], v[152:155], v[206:209], v[64:67]
	v_mfma_f32_16x16x32_bf16 v[120:123], v[148:151], v[164:167], v[120:123]
	v_mfma_f32_16x16x32_bf16 v[124:127], v[156:159], v[164:167], v[124:127]
	v_mfma_f32_16x16x32_bf16 v[100:103], v[148:151], v[172:175], v[100:103]
	v_mfma_f32_16x16x32_bf16 v[96:99], v[156:159], v[172:175], v[96:99]
	v_mfma_f32_16x16x32_bf16 v[84:87], v[148:151], v[202:205], v[84:87]
	v_mfma_f32_16x16x32_bf16 v[80:83], v[156:159], v[202:205], v[80:83]
	v_mfma_f32_16x16x32_bf16 v[68:71], v[148:151], v[210:213], v[68:71]
	v_mfma_f32_16x16x32_bf16 v[64:67], v[156:159], v[210:213], v[64:67]
	s_barrier
	s_add_i32 s55, s49, s28
	v_lshl_add_u64 v[196:197], s[22:23], 0, v[178:179]
	s_mov_b32 m0, s55
	ds_read_b128 v[160:163], v201 offset:16384
	ds_read_b128 v[164:167], v201 offset:17408
	ds_read_b128 v[168:171], v201 offset:18432
	ds_read_b128 v[172:175], v201 offset:19456
	ds_read_b128 v[192:195], v201 offset:20480
	ds_read_b128 v[202:205], v201 offset:21504
	ds_read_b128 v[206:209], v201 offset:22528
	ds_read_b128 v[210:213], v201 offset:23552
	global_load_lds_dwordx4 v[196:197], off
	s_add_i32 m0, s55, 0x2000
	s_add_u32 s56, s22, 0x40000
	v_lshl_add_u64 v[214:215], s[22:23], 0, v[176:177]
	s_addc_u32 s57, s23, 0
	s_add_i32 s55, s50, s28
	global_load_lds_dwordx4 v[214:215], off
	v_lshl_add_u64 v[216:217], s[56:57], 0, v[178:179]
	s_mov_b32 m0, s55
	v_lshl_add_u64 v[218:219], s[26:27], 0, v[176:177]
	global_load_lds_dwordx4 v[216:217], off
	v_lshl_add_u64 v[216:217], s[56:57], 0, v[176:177]
	s_add_i32 m0, s55, 0x2000
	s_nop 0
	global_load_lds_dwordx4 v[216:217], off
	v_lshl_add_u64 v[216:217], s[26:27], 0, v[178:179]
	s_mov_b32 m0, s29
	s_nop 0
	global_load_lds_dwordx4 v[216:217], off
	s_mov_b32 m0, s33
	s_nop 0
	global_load_lds_dwordx4 v[218:219], off
	s_waitcnt vmcnt(8)
	s_waitcnt lgkmcnt(0)
	s_barrier
; #define PG8_STAGE(bufoff, gbase, voff) do { _Pragma("unroll") for (int _i = 0; _i < 2; ++_i) \
;         __builtin_amdgcn_global_load_lds((const unsigned*)((const char*)(gbase) + (voff)[_i]), (PG8_LAS unsigned*)(lds + (bufoff) + ldsw + _i * 8192), 16, 0, 0); } while (0)
; #define PG8_LDA(dst, b, h) do { _Pragma("unroll") for (int m = 0; m < 4; ++m) _Pragma("unroll") for (int k = 0; k < 2; ++k) dst[m][k] = *(const PG8_LAS bf16x8*)(lds + PG8_SA(b, h) + aoff + m * 2048 + k * 1024); } while (0)
; #define PG8_LDB(dst, b, h) do { _Pragma("unroll") for (int n = 0; n < 2; ++n) _Pragma("unroll") for (int k = 0; k < 2; ++k) dst[n][k] = *(const PG8_LAS bf16x8*)(lds + PG8_SB(b, h) + boff + n * 2048 + k * 1024); } while (0)
; #define PG8_WAIT_V(n) asm volatile("s_waitcnt vmcnt(" #n ")" ::: "memory")
; #define PG8_WAIT_L(n) asm volatile("s_waitcnt lgkmcnt(" #n ")" ::: "memory")
; #define PG8_BAR __builtin_amdgcn_s_barrier()
; #define PG8_SCHED __builtin_amdgcn_sched_barrier(0)
;     ...
;             PG8_LDA(At, 0, 1); PG8_STAGE(PG8_SB(0, 0), b2, voffB); PG8_STAGE(PG8_SB(0, 1), b2 + hstepB, voffB); PG8_STAGE(PG8_SA(0, 0), a2, voffA);
;             PG8_WAIT_V(8); PG8_WAIT_L(0); PG8_BAR; PG8_MMA(1, 0, At, B0); PG8_MMA(1, 1, At, B1); PG8_BAR; PG8_SCHED;
;             PG8_LDB(B0, 1, 0); PG8_LDB(B1, 1, 1); PG8_SCHED; PG8_LDA(At, 1, 0); PG8_STAGE(PG8_SA(0, 1), a2 + hstep, voffA);
;             PG8_WAIT_V(8); PG8_WAIT_L(0); PG8_BAR; PG8_MMA(0, 0, At, B0); PG8_MMA(0, 1, At, B1); PG8_BAR; PG8_SCHED;
;             PG8_LDA(At, 1, 1); PG8_STAGE(PG8_SB(1, 0), b3, voffB); PG8_STAGE(PG8_SB(1, 1), b3 + hstepB, voffB); PG8_STAGE(PG8_SA(1, 0), a3, voffA);
;             PG8_WAIT_V(8); PG8_WAIT_L(0); PG8_BAR; PG8_MMA(1, 0, At, B0); PG8_MMA(1, 1, At, B1); PG8_BAR; PG8_SCHED;
	s_waitcnt lgkmcnt(0)
	v_mfma_f32_16x16x32_bf16 v[60:63], v[128:131], v[160:163], v[60:63]
	v_mfma_f32_16x16x32_bf16 v[52:55], v[136:139], v[160:163], v[52:55]
	v_mfma_f32_16x16x32_bf16 v[44:47], v[128:131], v[168:171], v[44:47]
	v_mfma_f32_16x16x32_bf16 v[36:39], v[136:139], v[168:171], v[36:39]
	v_mfma_f32_16x16x32_bf16 v[28:31], v[128:131], v[192:195], v[28:31]
	v_mfma_f32_16x16x32_bf16 v[20:23], v[136:139], v[192:195], v[20:23]
	v_mfma_f32_16x16x32_bf16 v[8:11], v[128:131], v[206:209], v[8:11]
	v_mfma_f32_16x16x32_bf16 v[0:3], v[136:139], v[206:209], v[0:3]
	v_mfma_f32_16x16x32_bf16 v[60:63], v[132:135], v[164:167], v[60:63]
	v_mfma_f32_16x16x32_bf16 v[52:55], v[140:143], v[164:167], v[52:55]
	v_mfma_f32_16x16x32_bf16 v[44:47], v[132:135], v[172:175], v[44:47]
	v_mfma_f32_16x16x32_bf16 v[36:39], v[140:143], v[172:175], v[36:39]
	v_mfma_f32_16x16x32_bf16 v[28:31], v[132:135], v[202:205], v[28:31]
	v_mfma_f32_16x16x32_bf16 v[20:23], v[140:143], v[202:205], v[20:23]
	v_mfma_f32_16x16x32_bf16 v[8:11], v[132:135], v[210:213], v[8:11]
	v_mfma_f32_16x16x32_bf16 v[0:3], v[140:143], v[210:213], v[0:3]
	v_mfma_f32_16x16x32_bf16 v[56:59], v[144:147], v[160:163], v[56:59]
	v_mfma_f32_16x16x32_bf16 v[48:51], v[152:155], v[160:163], v[48:51]
	v_mfma_f32_16x16x32_bf16 v[40:43], v[144:147], v[168:171], v[40:43]
	v_mfma_f32_16x16x32_bf16 v[32:35], v[152:155], v[168:171], v[32:35]
	v_mfma_f32_16x16x32_bf16 v[24:27], v[144:147], v[192:195], v[24:27]
	v_mfma_f32_16x16x32_bf16 v[16:19], v[152:155], v[192:195], v[16:19]
	v_mfma_f32_16x16x32_bf16 v[4:7], v[144:147], v[206:209], v[4:7]
	v_mfma_f32_16x16x32_bf16 v[12:15], v[152:155], v[206:209], v[12:15]
	v_mfma_f32_16x16x32_bf16 v[56:59], v[148:151], v[164:167], v[56:59]
	v_mfma_f32_16x16x32_bf16 v[48:51], v[156:159], v[164:167], v[48:51]
	v_mfma_f32_16x16x32_bf16 v[40:43], v[148:151], v[172:175], v[40:43]
	v_mfma_f32_16x16x32_bf16 v[32:35], v[156:159], v[172:175], v[32:35]
	v_mfma_f32_16x16x32_bf16 v[24:27], v[148:151], v[202:205], v[24:27]
	v_mfma_f32_16x16x32_bf16 v[16:19], v[156:159], v[202:205], v[16:19]
	v_mfma_f32_16x16x32_bf16 v[4:7], v[148:151], v[210:213], v[4:7]
	v_mfma_f32_16x16x32_bf16 v[12:15], v[156:159], v[210:213], v[12:15]
	s_barrier
	s_add_i32 s55, 0, 0x18000
	s_add_i32 s56, 0, 0x1c000
	v_add_u32_e32 v140, s55, v199
	v_add_u32_e32 v156, s56, v199
	ds_read_b128 v[128:131], v140
	ds_read_b128 v[132:135], v140 offset:1024
	ds_read_b128 v[136:139], v140 offset:2048
	ds_read_b128 v[140:143], v140 offset:3072
	ds_read_b128 v[144:147], v156
	ds_read_b128 v[148:151], v156 offset:1024
	ds_read_b128 v[152:155], v156 offset:2048
	ds_read_b128 v[156:159], v156 offset:3072
	s_add_u32 s26, s26, 0x40000
	s_addc_u32 s27, s27, 0
	s_mov_b32 m0, s36
	v_lshl_add_u64 v[220:221], s[26:27], 0, v[178:179]
	ds_read_b128 v[160:163], v201 offset:32768
	ds_read_b128 v[164:167], v201 offset:33792
	ds_read_b128 v[168:171], v201 offset:34816
	ds_read_b128 v[172:175], v201 offset:35840
	ds_read_b128 v[192:195], v201 offset:36864
	ds_read_b128 v[202:205], v201 offset:37888
	ds_read_b128 v[206:209], v201 offset:38912
	ds_read_b128 v[210:213], v201 offset:39936
	global_load_lds_dwordx4 v[220:221], off
	v_lshl_add_u64 v[220:221], s[26:27], 0, v[176:177]
	s_mov_b32 m0, s37
	s_nop 0
	global_load_lds_dwordx4 v[220:221], off
	s_waitcnt vmcnt(8)
	s_waitcnt lgkmcnt(0)
	s_barrier
	s_waitcnt lgkmcnt(0)
	v_mfma_f32_16x16x32_bf16 v[112:115], v[128:131], v[160:163], v[112:115]
	v_mfma_f32_16x16x32_bf16 v[116:119], v[136:139], v[160:163], v[116:119]
	v_mfma_f32_16x16x32_bf16 v[108:111], v[128:131], v[168:171], v[108:111]
	v_mfma_f32_16x16x32_bf16 v[104:107], v[136:139], v[168:171], v[104:107]
	v_mfma_f32_16x16x32_bf16 v[92:95], v[128:131], v[192:195], v[92:95]
	v_mfma_f32_16x16x32_bf16 v[88:91], v[136:139], v[192:195], v[88:91]
	v_mfma_f32_16x16x32_bf16 v[76:79], v[128:131], v[206:209], v[76:79]
	v_mfma_f32_16x16x32_bf16 v[72:75], v[136:139], v[206:209], v[72:75]
	v_mfma_f32_16x16x32_bf16 v[112:115], v[132:135], v[164:167], v[112:115]
	v_mfma_f32_16x16x32_bf16 v[116:119], v[140:143], v[164:167], v[116:119]
	v_mfma_f32_16x16x32_bf16 v[108:111], v[132:135], v[172:175], v[108:111]
	v_mfma_f32_16x16x32_bf16 v[104:107], v[140:143], v[172:175], v[104:107]
	v_mfma_f32_16x16x32_bf16 v[92:95], v[132:135], v[202:205], v[92:95]
	v_mfma_f32_16x16x32_bf16 v[88:91], v[140:143], v[202:205], v[88:91]
	v_mfma_f32_16x16x32_bf16 v[76:79], v[132:135], v[210:213], v[76:79]
	v_mfma_f32_16x16x32_bf16 v[72:75], v[140:143], v[210:213], v[72:75]
	v_mfma_f32_16x16x32_bf16 v[120:123], v[144:147], v[160:163], v[120:123]
	v_mfma_f32_16x16x32_bf16 v[124:127], v[152:155], v[160:163], v[124:127]
	v_mfma_f32_16x16x32_bf16 v[100:103], v[144:147], v[168:171], v[100:103]
	v_mfma_f32_16x16x32_bf16 v[96:99], v[152:155], v[168:171], v[96:99]
	v_mfma_f32_16x16x32_bf16 v[84:87], v[144:147], v[192:195], v[84:87]
	v_mfma_f32_16x16x32_bf16 v[80:83], v[152:155], v[192:195], v[80:83]
	v_mfma_f32_16x16x32_bf16 v[68:71], v[144:147], v[206:209], v[68:71]
	v_mfma_f32_16x16x32_bf16 v[64:67], v[152:155], v[206:209], v[64:67]
	v_mfma_f32_16x16x32_bf16 v[120:123], v[148:151], v[164:167], v[120:123]
	v_mfma_f32_16x16x32_bf16 v[124:127], v[156:159], v[164:167], v[124:127]
	v_mfma_f32_16x16x32_bf16 v[100:103], v[148:151], v[172:175], v[100:103]
	v_mfma_f32_16x16x32_bf16 v[96:99], v[156:159], v[172:175], v[96:99]
	v_mfma_f32_16x16x32_bf16 v[84:87], v[148:151], v[202:205], v[84:87]
	v_mfma_f32_16x16x32_bf16 v[80:83], v[156:159], v[202:205], v[80:83]
	v_mfma_f32_16x16x32_bf16 v[68:71], v[148:151], v[210:213], v[68:71]
	v_mfma_f32_16x16x32_bf16 v[64:67], v[156:159], v[210:213], v[64:67]
	s_barrier
; #define PG8_STAGE(bufoff, gbase, voff) do { _Pragma("unroll") for (int _i = 0; _i < 2; ++_i) \
;         __builtin_amdgcn_global_load_lds((const unsigned*)((const char*)(gbase) + (voff)[_i]), (PG8_LAS unsigned*)(lds + (bufoff) + ldsw + _i * 8192), 16, 0, 0); } while (0)
; #define PG8_LDA(dst, b, h) do { _Pragma("unroll") for (int m = 0; m < 4; ++m) _Pragma("unroll") for (int k = 0; k < 2; ++k) dst[m][k] = *(const PG8_LAS bf16x8*)(lds + PG8_SA(b, h) + aoff + m * 2048 + k * 1024); } while (0)
; #define PG8_WAIT_V(n) asm volatile("s_waitcnt vmcnt(" #n ")" ::: "memory")
; #define PG8_WAIT_L(n) asm volatile("s_waitcnt lgkmcnt(" #n ")" ::: "memory")
; #define PG8_BAR __builtin_amdgcn_s_barrier()
; #define PG8_SCHED __builtin_amdgcn_sched_barrier(0)
;     ...
;             PG8_LDA(At, 1, 1); PG8_STAGE(PG8_SB(1, 0), b3, voffB); PG8_STAGE(PG8_SB(1, 1), b3 + hstepB, voffB); PG8_STAGE(PG8_SA(1, 0), a3, voffA);
;             PG8_WAIT_V(8); PG8_WAIT_L(0); PG8_BAR; PG8_MMA(1, 0, At, B0); PG8_MMA(1, 1, At, B1); PG8_BAR; PG8_SCHED;
;         }
	s_add_i32 s26, s55, s28
	v_lshl_add_u64 v[196:197], v[196:197], 0, s[8:9]
	s_mov_b32 m0, s26
	ds_read_b128 v[160:163], v201 offset:49152
	ds_read_b128 v[164:167], v201 offset:50176
	ds_read_b128 v[168:171], v201 offset:51200
	ds_read_b128 v[172:175], v201 offset:52224
	ds_read_b128 v[192:195], v201 offset:53248
	ds_read_b128 v[202:205], v201 offset:54272
	ds_read_b128 v[206:209], v201 offset:55296
	ds_read_b128 v[210:213], v201 offset:56320
	global_load_lds_dwordx4 v[196:197], off
	s_add_i32 m0, s26, 0x2000
	s_add_u32 s22, s22, 0x40080
	v_lshl_add_u64 v[196:197], v[214:215], 0, s[8:9]
	s_addc_u32 s23, s23, 0
	s_add_i32 s26, s56, s28
	global_load_lds_dwordx4 v[196:197], off
	v_lshl_add_u64 v[196:197], s[22:23], 0, v[178:179]
	s_mov_b32 m0, s26
	s_nop 0
	global_load_lds_dwordx4 v[196:197], off
	v_lshl_add_u64 v[196:197], s[22:23], 0, v[176:177]
	s_add_i32 m0, s26, 0x2000
	s_nop 0
	global_load_lds_dwordx4 v[196:197], off
	v_lshl_add_u64 v[196:197], v[216:217], 0, s[8:9]
	s_mov_b32 m0, s41
	s_nop 0
	global_load_lds_dwordx4 v[196:197], off
	v_lshl_add_u64 v[196:197], v[218:219], 0, s[8:9]
	s_mov_b32 m0, s42
	s_nop 0
	global_load_lds_dwordx4 v[196:197], off
	s_waitcnt vmcnt(8)
	s_waitcnt lgkmcnt(0)
	s_barrier
	s_waitcnt lgkmcnt(0)
	v_mfma_f32_16x16x32_bf16 v[60:63], v[128:131], v[160:163], v[60:63]
	v_mfma_f32_16x16x32_bf16 v[52:55], v[136:139], v[160:163], v[52:55]
	v_mfma_f32_16x16x32_bf16 v[44:47], v[128:131], v[168:171], v[44:47]
	v_mfma_f32_16x16x32_bf16 v[36:39], v[136:139], v[168:171], v[36:39]
	v_mfma_f32_16x16x32_bf16 v[28:31], v[128:131], v[192:195], v[28:31]
	v_mfma_f32_16x16x32_bf16 v[20:23], v[136:139], v[192:195], v[20:23]
	v_mfma_f32_16x16x32_bf16 v[8:11], v[128:131], v[206:209], v[8:11]
	v_mfma_f32_16x16x32_bf16 v[0:3], v[136:139], v[206:209], v[0:3]
	v_mfma_f32_16x16x32_bf16 v[60:63], v[132:135], v[164:167], v[60:63]
	v_mfma_f32_16x16x32_bf16 v[52:55], v[140:143], v[164:167], v[52:55]
	v_mfma_f32_16x16x32_bf16 v[44:47], v[132:135], v[172:175], v[44:47]
	v_mfma_f32_16x16x32_bf16 v[36:39], v[140:143], v[172:175], v[36:39]
	v_mfma_f32_16x16x32_bf16 v[28:31], v[132:135], v[202:205], v[28:31]
	v_mfma_f32_16x16x32_bf16 v[20:23], v[140:143], v[202:205], v[20:23]
	v_mfma_f32_16x16x32_bf16 v[8:11], v[132:135], v[210:213], v[8:11]
	v_mfma_f32_16x16x32_bf16 v[0:3], v[140:143], v[210:213], v[0:3]
	v_mfma_f32_16x16x32_bf16 v[56:59], v[144:147], v[160:163], v[56:59]
	v_mfma_f32_16x16x32_bf16 v[48:51], v[152:155], v[160:163], v[48:51]
	v_mfma_f32_16x16x32_bf16 v[40:43], v[144:147], v[168:171], v[40:43]
	v_mfma_f32_16x16x32_bf16 v[32:35], v[152:155], v[168:171], v[32:35]
	v_mfma_f32_16x16x32_bf16 v[24:27], v[144:147], v[192:195], v[24:27]
	v_mfma_f32_16x16x32_bf16 v[16:19], v[152:155], v[192:195], v[16:19]
	v_mfma_f32_16x16x32_bf16 v[4:7], v[144:147], v[206:209], v[4:7]
	v_mfma_f32_16x16x32_bf16 v[12:15], v[152:155], v[206:209], v[12:15]
	v_mfma_f32_16x16x32_bf16 v[56:59], v[148:151], v[164:167], v[56:59]
	v_mfma_f32_16x16x32_bf16 v[48:51], v[156:159], v[164:167], v[48:51]
	v_mfma_f32_16x16x32_bf16 v[40:43], v[148:151], v[172:175], v[40:43]
	v_mfma_f32_16x16x32_bf16 v[32:35], v[156:159], v[172:175], v[32:35]
	v_mfma_f32_16x16x32_bf16 v[24:27], v[148:151], v[202:205], v[24:27]
	v_mfma_f32_16x16x32_bf16 v[16:19], v[156:159], v[202:205], v[16:19]
	v_mfma_f32_16x16x32_bf16 v[4:7], v[148:151], v[210:213], v[4:7]
	v_mfma_f32_16x16x32_bf16 v[12:15], v[156:159], v[210:213], v[12:15]
	s_barrier
	s_add_i32 s54, s54, 2
	s_add_u32 s24, s24, 0x100
	s_addc_u32 s25, s25, 0
	s_add_u32 s52, s52, 0x100
	s_addc_u32 s53, s53, 0
	s_cmp_gt_u32 s54, 13
	s_cbranch_scc0 .LBB0_434
	s_and_b64 vcc, exec, s[10:11]
	s_cbranch_vccz .LBB0_437
	s_barrier

; #define PG8_STAGE(bufoff, gbase, voff) do { _Pragma("unroll") for (int _i = 0; _i < 2; ++_i) \
;         __builtin_amdgcn_global_load_lds((const unsigned*)((const char*)(gbase) + (voff)[_i]), (PG8_LAS unsigned*)(lds + (bufoff) + ldsw + _i * 8192), 16, 0, 0); } while (0)
; #define PG8_LDA(dst, b, h) do { _Pragma("unroll") for (int m = 0; m < 4; ++m) _Pragma("unroll") for (int k = 0; k < 2; ++k) dst[m][k] = *(const PG8_LAS bf16x8*)(lds + PG8_SA(b, h) + aoff + m * 2048 + k * 1024); } while (0)
; #define PG8_WAIT_V(n) asm volatile("s_waitcnt vmcnt(" #n ")" ::: "memory")
; #define PG8_WAIT_L(n) asm volatile("s_waitcnt lgkmcnt(" #n ")" ::: "memory")
; #define PG8_BAR __builtin_amdgcn_s_barrier()
; #define PG8_SCHED __builtin_amdgcn_sched_barrier(0)
;     __device__ __forceinline__ void operator()(const f32x4 (&acc)[2][2][4][2], const Unit& u, int wr, int wc, int fr, int fq, const bool reuse, PG8_LAS float* rscr, PG8_LAS const float* gains) const {
;     ...
;                 f32x4 rs4[2][4];
; #pragma unroll
;                 for (int ai = 0; ai < 2; ++ai)
; #pragma unroll
;                     for (int m = 0; m < 4; ++m) { const int r = u.pm * BM + ai * HALF + wr * 64 + m * 16 + fr; rs4[ai][m] = *(const f32x4*)(rs + (size_t)(row_base + r) * 16 + 4 * fq); }
;     ...
;             PG8_WAIT_V(8); PG8_WAIT_L(0); PG8_BAR; PG8_MMA(0, 0, At, B0); PG8_MMA(0, 1, At, B1); PG8_BAR; PG8_SCHED;
;             PG8_LDA(At, 0, 1); PG8_STAGE(PG8_SB(0, 0), b2, voffB); PG8_STAGE(PG8_SB(0, 1), b2 + hstepB, voffB); PG8_STAGE(PG8_SA(0, 0), a2, voffA);
;             PG8_WAIT_V(8); PG8_WAIT_L(0); PG8_BAR; PG8_MMA(1, 0, At, B0); PG8_MMA(1, 1, At, B1); PG8_BAR; PG8_SCHED;
.Lpkb_da:
	s_waitcnt lgkmcnt(0)
	s_barrier
	s_waitcnt lgkmcnt(0)
	v_mfma_f32_16x16x32_f16 v[132:135], v[112:115], v[160:163], v[132:135]
	v_mfma_f32_16x16x32_f16 v[128:131], v[120:123], v[160:163], v[128:131]
	v_mfma_f32_16x16x32_f16 v[100:103], v[112:115], v[168:171], v[100:103]
	v_mfma_f32_16x16x32_f16 v[96:99], v[120:123], v[168:171], v[96:99]
	v_mfma_f32_16x16x32_f16 v[84:87], v[112:115], v[202:205], v[84:87]
	v_mfma_f32_16x16x32_f16 v[80:83], v[120:123], v[202:205], v[80:83]
	v_mfma_f32_16x16x32_f16 v[68:71], v[112:115], v[210:213], v[68:71]
	v_mfma_f32_16x16x32_f16 v[64:67], v[120:123], v[210:213], v[64:67]
	v_mfma_f32_16x16x32_f16 v[132:135], v[116:119], v[164:167], v[132:135]
	v_mfma_f32_16x16x32_f16 v[128:131], v[124:127], v[164:167], v[128:131]
	v_mfma_f32_16x16x32_f16 v[100:103], v[116:119], v[192:195], v[100:103]
	v_mfma_f32_16x16x32_f16 v[96:99], v[124:127], v[192:195], v[96:99]
	v_mfma_f32_16x16x32_f16 v[84:87], v[116:119], v[206:209], v[84:87]
	v_mfma_f32_16x16x32_f16 v[80:83], v[124:127], v[206:209], v[80:83]
	v_mfma_f32_16x16x32_f16 v[68:71], v[116:119], v[214:217], v[68:71]
	v_mfma_f32_16x16x32_f16 v[64:67], v[124:127], v[214:217], v[64:67]
	v_mfma_f32_16x16x32_f16 v[140:143], v[144:147], v[160:163], v[140:143]
	v_mfma_f32_16x16x32_f16 v[136:139], v[152:155], v[160:163], v[136:139]
	v_mfma_f32_16x16x32_f16 v[108:111], v[144:147], v[168:171], v[108:111]
	v_mfma_f32_16x16x32_f16 v[104:107], v[152:155], v[168:171], v[104:107]
	v_mfma_f32_16x16x32_f16 v[92:95], v[144:147], v[202:205], v[92:95]
	v_mfma_f32_16x16x32_f16 v[88:91], v[152:155], v[202:205], v[88:91]
	v_mfma_f32_16x16x32_f16 v[76:79], v[144:147], v[210:213], v[76:79]
	v_mfma_f32_16x16x32_f16 v[72:75], v[152:155], v[210:213], v[72:75]
	v_mfma_f32_16x16x32_f16 v[140:143], v[148:151], v[164:167], v[140:143]
	v_mfma_f32_16x16x32_f16 v[136:139], v[156:159], v[164:167], v[136:139]
	v_mfma_f32_16x16x32_f16 v[108:111], v[148:151], v[192:195], v[108:111]
	v_mfma_f32_16x16x32_f16 v[104:107], v[156:159], v[192:195], v[104:107]
	v_mfma_f32_16x16x32_f16 v[92:95], v[148:151], v[206:209], v[92:95]
	v_mfma_f32_16x16x32_f16 v[88:91], v[156:159], v[206:209], v[88:91]
	v_mfma_f32_16x16x32_f16 v[76:79], v[148:151], v[214:217], v[76:79]
	v_mfma_f32_16x16x32_f16 v[72:75], v[156:159], v[214:217], v[72:75]
	s_barrier
	s_add_i32 s57, s51, s28
	v_lshl_add_u64 v[218:219], s[22:23], 0, v[174:175]
	s_mov_b32 m0, s57
	ds_read_b128 v[160:163], v200 offset:16384
	ds_read_b128 v[164:167], v200 offset:17408
	ds_read_b128 v[168:171], v200 offset:18432
	ds_read_b128 v[192:195], v200 offset:19456
	ds_read_b128 v[202:205], v200 offset:20480
	ds_read_b128 v[206:209], v200 offset:21504
	ds_read_b128 v[210:213], v200 offset:22528
	ds_read_b128 v[214:217], v200 offset:23552
	global_load_lds_dwordx4 v[218:219], off
	s_add_i32 m0, s57, 0x2000
	s_add_u32 s58, s22, 0x10000
	v_lshl_add_u64 v[220:221], s[22:23], 0, v[178:179]
	s_addc_u32 s59, s23, 0
	s_add_i32 s57, s52, s28
	global_load_lds_dwordx4 v[220:221], off
	v_lshl_add_u64 v[222:223], s[58:59], 0, v[174:175]
	s_mov_b32 m0, s57
	v_lshl_add_u64 v[224:225], s[26:27], 0, v[176:177]
	global_load_lds_dwordx4 v[222:223], off
	v_lshl_add_u64 v[222:223], s[58:59], 0, v[178:179]
	s_add_i32 m0, s57, 0x2000
	s_nop 0
	global_load_lds_dwordx4 v[222:223], off
	v_lshl_add_u64 v[222:223], s[26:27], 0, v[172:173]
	s_mov_b32 m0, s29
	s_nop 0
	global_load_lds_dwordx4 v[222:223], off
	s_mov_b32 m0, s41
	s_nop 0
	global_load_lds_dwordx4 v[224:225], off
	s_cmp_eq_u32 s56, 10
	s_cbranch_scc0 .Lrs_n
	s_cmp_lg_u32 s54, s38
	s_cbranch_scc0 .Lrs_n
	s_bitset1_b32 s101, 17
	s_lshl_b32 s32, s54, 8
	s_add_i32 s32, s32, s45
	s_bfe_u32 vcc_lo, s29, 0x2000a
	s_and_b32 vcc_hi, vcc_lo, 1
	s_lshl_b32 vcc_hi, vcc_hi, 5
	s_lshr_b32 m0, vcc_lo, 1
	s_lshl_b32 m0, m0, 7
	s_add_i32 vcc_hi, vcc_hi, m0
	s_add_i32 s32, s32, vcc_hi
	v_or_b32_e32 v228, s32, v196
	v_add_u32_e32 v230, 16, v228
	v_lshlrev_b32_e32 v228, 6, v228
	v_lshlrev_b32_e32 v230, 6, v230
	v_mov_b32_e32 v229, 0
	v_mov_b32_e32 v231, 0
	v_lshl_add_u64 v[228:229], v[228:229], 0, v[182:183]
	v_lshl_add_u64 v[230:231], v[230:231], 0, v[182:183]
	s_lshl_b32 vcc_lo, vcc_lo, 11
	s_lshr_b32 vcc_hi, s29, 12
	s_lshl_b32 vcc_hi, vcc_hi, 13
	s_add_i32 vcc_lo, vcc_lo, vcc_hi
	s_add_i32 m0, vcc_lo, 0x22000
	s_nop 0
	global_load_lds_dwordx4 v[228:229], off
	s_add_i32 m0, m0, 0x400
	s_nop 0
	global_load_lds_dwordx4 v[230:231], off

; #define PG8_STAGE(bufoff, gbase, voff) do { _Pragma("unroll") for (int _i = 0; _i < 2; ++_i) \
;         __builtin_amdgcn_global_load_lds((const unsigned*)((const char*)(gbase) + (voff)[_i]), (PG8_LAS unsigned*)(lds + (bufoff) + ldsw + _i * 8192), 16, 0, 0); } while (0)
; #define PG8_LDA(dst, b, h) do { _Pragma("unroll") for (int m = 0; m < 4; ++m) _Pragma("unroll") for (int k = 0; k < 2; ++k) dst[m][k] = *(const PG8_LAS bf16x8*)(lds + PG8_SA(b, h) + aoff + m * 2048 + k * 1024); } while (0)
; #define PG8_LDB(dst, b, h) do { _Pragma("unroll") for (int n = 0; n < 2; ++n) _Pragma("unroll") for (int k = 0; k < 2; ++k) dst[n][k] = *(const PG8_LAS bf16x8*)(lds + PG8_SB(b, h) + boff + n * 2048 + k * 1024); } while (0)
; #define PG8_WAIT_V(n) asm volatile("s_waitcnt vmcnt(" #n ")" ::: "memory")
; #define PG8_WAIT_L(n) asm volatile("s_waitcnt lgkmcnt(" #n ")" ::: "memory")
; #define PG8_BAR __builtin_amdgcn_s_barrier()
; #define PG8_SCHED __builtin_amdgcn_sched_barrier(0)
;     ...
;             PG8_WAIT_V(8); PG8_WAIT_L(0); PG8_BAR; PG8_MMA(1, 0, At, B0); PG8_MMA(1, 1, At, B1); PG8_BAR; PG8_SCHED;
;             PG8_LDB(B0, 1, 0); PG8_LDB(B1, 1, 1); PG8_SCHED; PG8_LDA(At, 1, 0); PG8_STAGE(PG8_SA(0, 1), a2 + hstep, voffA);
;             PG8_WAIT_V(8); PG8_WAIT_L(0); PG8_BAR; PG8_MMA(0, 0, At, B0); PG8_MMA(0, 1, At, B1); PG8_BAR; PG8_SCHED;
.Lpkb_db:
	s_waitcnt lgkmcnt(0)
	s_barrier
	s_waitcnt lgkmcnt(0)
	v_mfma_f32_16x16x32_f16 v[52:55], v[112:115], v[160:163], v[52:55]
	v_mfma_f32_16x16x32_f16 v[48:51], v[120:123], v[160:163], v[48:51]
	v_mfma_f32_16x16x32_f16 v[36:39], v[112:115], v[168:171], v[36:39]
	v_mfma_f32_16x16x32_f16 v[32:35], v[120:123], v[168:171], v[32:35]
	v_mfma_f32_16x16x32_f16 v[20:23], v[112:115], v[202:205], v[20:23]
	v_mfma_f32_16x16x32_f16 v[16:19], v[120:123], v[202:205], v[16:19]
	v_mfma_f32_16x16x32_f16 v[4:7], v[112:115], v[210:213], v[4:7]
	v_mfma_f32_16x16x32_f16 v[0:3], v[120:123], v[210:213], v[0:3]
	v_mfma_f32_16x16x32_f16 v[52:55], v[116:119], v[164:167], v[52:55]
	v_mfma_f32_16x16x32_f16 v[48:51], v[124:127], v[164:167], v[48:51]
	v_mfma_f32_16x16x32_f16 v[36:39], v[116:119], v[192:195], v[36:39]
	v_mfma_f32_16x16x32_f16 v[32:35], v[124:127], v[192:195], v[32:35]
	v_mfma_f32_16x16x32_f16 v[20:23], v[116:119], v[206:209], v[20:23]
	v_mfma_f32_16x16x32_f16 v[16:19], v[124:127], v[206:209], v[16:19]
	v_mfma_f32_16x16x32_f16 v[4:7], v[116:119], v[214:217], v[4:7]
	v_mfma_f32_16x16x32_f16 v[0:3], v[124:127], v[214:217], v[0:3]
	v_mfma_f32_16x16x32_f16 v[60:63], v[144:147], v[160:163], v[60:63]
	v_mfma_f32_16x16x32_f16 v[56:59], v[152:155], v[160:163], v[56:59]
	v_mfma_f32_16x16x32_f16 v[44:47], v[144:147], v[168:171], v[44:47]
	v_mfma_f32_16x16x32_f16 v[40:43], v[152:155], v[168:171], v[40:43]
	v_mfma_f32_16x16x32_f16 v[28:31], v[144:147], v[202:205], v[28:31]
	v_mfma_f32_16x16x32_f16 v[24:27], v[152:155], v[202:205], v[24:27]
	v_mfma_f32_16x16x32_f16 v[12:15], v[144:147], v[210:213], v[12:15]
	v_mfma_f32_16x16x32_f16 v[8:11], v[152:155], v[210:213], v[8:11]
	v_mfma_f32_16x16x32_f16 v[60:63], v[148:151], v[164:167], v[60:63]
	v_mfma_f32_16x16x32_f16 v[56:59], v[156:159], v[164:167], v[56:59]
	v_mfma_f32_16x16x32_f16 v[44:47], v[148:151], v[192:195], v[44:47]
	v_mfma_f32_16x16x32_f16 v[40:43], v[156:159], v[192:195], v[40:43]
	v_mfma_f32_16x16x32_f16 v[28:31], v[148:151], v[206:209], v[28:31]
	v_mfma_f32_16x16x32_f16 v[24:27], v[156:159], v[206:209], v[24:27]
	v_mfma_f32_16x16x32_f16 v[12:15], v[148:151], v[214:217], v[12:15]
	v_mfma_f32_16x16x32_f16 v[8:11], v[156:159], v[214:217], v[8:11]
	s_barrier
	s_add_i32 s57, 0, 0x18000
	s_add_i32 s58, 0, 0x1c000
	v_add_u32_e32 v124, s57, v197
	v_add_u32_e32 v156, s58, v197
	ds_read_b128 v[112:115], v124
	ds_read_b128 v[116:119], v124 offset:1024
	ds_read_b128 v[120:123], v124 offset:2048
	ds_read_b128 v[124:127], v124 offset:3072
	ds_read_b128 v[144:147], v156
	ds_read_b128 v[148:151], v156 offset:1024
	ds_read_b128 v[152:155], v156 offset:2048
	ds_read_b128 v[156:159], v156 offset:3072
	s_add_u32 s26, s26, 0x40000
	s_addc_u32 s27, s27, 0
	s_mov_b32 m0, s42
	v_lshl_add_u64 v[226:227], s[26:27], 0, v[172:173]
	ds_read_b128 v[160:163], v200 offset:32768
	ds_read_b128 v[164:167], v200 offset:33792
	ds_read_b128 v[168:171], v200 offset:34816
	ds_read_b128 v[192:195], v200 offset:35840
	ds_read_b128 v[202:205], v200 offset:36864
	ds_read_b128 v[206:209], v200 offset:37888
	ds_read_b128 v[210:213], v200 offset:38912
	ds_read_b128 v[214:217], v200 offset:39936
	global_load_lds_dwordx4 v[226:227], off
	v_lshl_add_u64 v[226:227], s[26:27], 0, v[176:177]
	s_mov_b32 m0, s43
	s_nop 0
	global_load_lds_dwordx4 v[226:227], off
	s_bfe_u32 vcc_lo, s101, 0x20010
	s_cmp_eq_u32 vcc_lo, 0
	s_cbranch_scc1 .Lpkb_w8c
	s_cmp_eq_u32 vcc_lo, 1
	s_cbranch_scc1 .Lpkb_w9c
	s_cmp_eq_u32 vcc_lo, 2
	s_cbranch_scc1 .Lpkb_w10c
	s_waitcnt vmcnt(11)
	s_branch .Lpkb_dc

; #define PG8_STAGE(bufoff, gbase, voff) do { _Pragma("unroll") for (int _i = 0; _i < 2; ++_i) \
;         __builtin_amdgcn_global_load_lds((const unsigned*)((const char*)(gbase) + (voff)[_i]), (PG8_LAS unsigned*)(lds + (bufoff) + ldsw + _i * 8192), 16, 0, 0); } while (0)
; #define PG8_LDA(dst, b, h) do { _Pragma("unroll") for (int m = 0; m < 4; ++m) _Pragma("unroll") for (int k = 0; k < 2; ++k) dst[m][k] = *(const PG8_LAS bf16x8*)(lds + PG8_SA(b, h) + aoff + m * 2048 + k * 1024); } while (0)
; #define PG8_WAIT_V(n) asm volatile("s_waitcnt vmcnt(" #n ")" ::: "memory")
; #define PG8_WAIT_L(n) asm volatile("s_waitcnt lgkmcnt(" #n ")" ::: "memory")
; #define PG8_BAR __builtin_amdgcn_s_barrier()
; #define PG8_SCHED __builtin_amdgcn_sched_barrier(0)
;     ...
;             PG8_WAIT_V(8); PG8_WAIT_L(0); PG8_BAR; PG8_MMA(0, 0, At, B0); PG8_MMA(0, 1, At, B1); PG8_BAR; PG8_SCHED;
;             PG8_LDA(At, 1, 1); PG8_STAGE(PG8_SB(1, 0), b3, voffB); PG8_STAGE(PG8_SB(1, 1), b3 + hstepB, voffB); PG8_STAGE(PG8_SA(1, 0), a3, voffA);
;             PG8_WAIT_V(8); PG8_WAIT_L(0); PG8_BAR; PG8_MMA(1, 0, At, B0); PG8_MMA(1, 1, At, B1); PG8_BAR; PG8_SCHED;
.Lpkb_dc:
	s_waitcnt lgkmcnt(0)
	s_barrier
	s_waitcnt lgkmcnt(0)
	v_mfma_f32_16x16x32_f16 v[132:135], v[112:115], v[160:163], v[132:135]
	v_mfma_f32_16x16x32_f16 v[128:131], v[120:123], v[160:163], v[128:131]
	v_mfma_f32_16x16x32_f16 v[100:103], v[112:115], v[168:171], v[100:103]
	v_mfma_f32_16x16x32_f16 v[96:99], v[120:123], v[168:171], v[96:99]
	v_mfma_f32_16x16x32_f16 v[84:87], v[112:115], v[202:205], v[84:87]
	v_mfma_f32_16x16x32_f16 v[80:83], v[120:123], v[202:205], v[80:83]
	v_mfma_f32_16x16x32_f16 v[68:71], v[112:115], v[210:213], v[68:71]
	v_mfma_f32_16x16x32_f16 v[64:67], v[120:123], v[210:213], v[64:67]
	v_mfma_f32_16x16x32_f16 v[132:135], v[116:119], v[164:167], v[132:135]
	v_mfma_f32_16x16x32_f16 v[128:131], v[124:127], v[164:167], v[128:131]
	v_mfma_f32_16x16x32_f16 v[100:103], v[116:119], v[192:195], v[100:103]
	v_mfma_f32_16x16x32_f16 v[96:99], v[124:127], v[192:195], v[96:99]
	v_mfma_f32_16x16x32_f16 v[84:87], v[116:119], v[206:209], v[84:87]
	v_mfma_f32_16x16x32_f16 v[80:83], v[124:127], v[206:209], v[80:83]
	v_mfma_f32_16x16x32_f16 v[68:71], v[116:119], v[214:217], v[68:71]
	v_mfma_f32_16x16x32_f16 v[64:67], v[124:127], v[214:217], v[64:67]
	v_mfma_f32_16x16x32_f16 v[140:143], v[144:147], v[160:163], v[140:143]
	v_mfma_f32_16x16x32_f16 v[136:139], v[152:155], v[160:163], v[136:139]
	v_mfma_f32_16x16x32_f16 v[108:111], v[144:147], v[168:171], v[108:111]
	v_mfma_f32_16x16x32_f16 v[104:107], v[152:155], v[168:171], v[104:107]
	v_mfma_f32_16x16x32_f16 v[92:95], v[144:147], v[202:205], v[92:95]
	v_mfma_f32_16x16x32_f16 v[88:91], v[152:155], v[202:205], v[88:91]
	v_mfma_f32_16x16x32_f16 v[76:79], v[144:147], v[210:213], v[76:79]
	v_mfma_f32_16x16x32_f16 v[72:75], v[152:155], v[210:213], v[72:75]
	v_mfma_f32_16x16x32_f16 v[140:143], v[148:151], v[164:167], v[140:143]
	v_mfma_f32_16x16x32_f16 v[136:139], v[156:159], v[164:167], v[136:139]
	v_mfma_f32_16x16x32_f16 v[108:111], v[148:151], v[192:195], v[108:111]
	v_mfma_f32_16x16x32_f16 v[104:107], v[156:159], v[192:195], v[104:107]
	v_mfma_f32_16x16x32_f16 v[92:95], v[148:151], v[206:209], v[92:95]
	v_mfma_f32_16x16x32_f16 v[88:91], v[156:159], v[206:209], v[88:91]
	v_mfma_f32_16x16x32_f16 v[76:79], v[148:151], v[214:217], v[76:79]
	v_mfma_f32_16x16x32_f16 v[72:75], v[156:159], v[214:217], v[72:75]
	s_barrier
	s_add_i32 s26, s57, s28
	v_lshl_add_u64 v[218:219], v[218:219], 0, s[10:11]
	s_mov_b32 m0, s26
	ds_read_b128 v[160:163], v200 offset:49152
	ds_read_b128 v[164:167], v200 offset:50176
	ds_read_b128 v[168:171], v200 offset:51200
	ds_read_b128 v[192:195], v200 offset:52224
	ds_read_b128 v[202:205], v200 offset:53248
	ds_read_b128 v[206:209], v200 offset:54272
	ds_read_b128 v[210:213], v200 offset:55296
	ds_read_b128 v[214:217], v200 offset:56320
	global_load_lds_dwordx4 v[218:219], off
	s_add_i32 m0, s26, 0x2000
	s_add_u32 s22, s22, 0x10080
	v_lshl_add_u64 v[218:219], v[220:221], 0, s[10:11]
	s_addc_u32 s23, s23, 0
	s_add_i32 s26, s58, s28
	global_load_lds_dwordx4 v[218:219], off
	v_lshl_add_u64 v[218:219], s[22:23], 0, v[174:175]
	s_mov_b32 m0, s26
	s_nop 0
	global_load_lds_dwordx4 v[218:219], off
	v_lshl_add_u64 v[218:219], s[22:23], 0, v[178:179]
	s_add_i32 m0, s26, 0x2000
	s_nop 0
	global_load_lds_dwordx4 v[218:219], off
	v_lshl_add_u64 v[218:219], v[222:223], 0, s[10:11]
	s_mov_b32 m0, s48
	s_nop 0
	global_load_lds_dwordx4 v[218:219], off
	v_lshl_add_u64 v[218:219], v[224:225], 0, s[10:11]
	s_mov_b32 m0, s49
	s_nop 0
	global_load_lds_dwordx4 v[218:219], off
	s_bitcmp1_b32 s101, 17
	s_cbranch_scc0 .Lpkb_w8e
	s_waitcnt vmcnt(10)
	s_branch .Lpkb_de

; #define PG8_WAIT_V(n) asm volatile("s_waitcnt vmcnt(" #n ")" ::: "memory")
; #define PG8_WAIT_L(n) asm volatile("s_waitcnt lgkmcnt(" #n ")" ::: "memory")
; #define PG8_BAR __builtin_amdgcn_s_barrier()
; #define PG8_SCHED __builtin_amdgcn_sched_barrier(0)
;     ...
;             PG8_WAIT_V(8); PG8_WAIT_L(0); PG8_BAR; PG8_MMA(1, 0, At, B0); PG8_MMA(1, 1, At, B1); PG8_BAR; PG8_SCHED;
;         }
.Lpkb_de:
	s_waitcnt lgkmcnt(0)
	s_barrier
	s_waitcnt lgkmcnt(0)
	v_mfma_f32_16x16x32_f16 v[52:55], v[112:115], v[160:163], v[52:55]
	v_mfma_f32_16x16x32_f16 v[48:51], v[120:123], v[160:163], v[48:51]
	v_mfma_f32_16x16x32_f16 v[36:39], v[112:115], v[168:171], v[36:39]
	v_mfma_f32_16x16x32_f16 v[32:35], v[120:123], v[168:171], v[32:35]
	v_mfma_f32_16x16x32_f16 v[20:23], v[112:115], v[202:205], v[20:23]
	v_mfma_f32_16x16x32_f16 v[16:19], v[120:123], v[202:205], v[16:19]
	v_mfma_f32_16x16x32_f16 v[4:7], v[112:115], v[210:213], v[4:7]
	v_mfma_f32_16x16x32_f16 v[0:3], v[120:123], v[210:213], v[0:3]
	v_mfma_f32_16x16x32_f16 v[52:55], v[116:119], v[164:167], v[52:55]
	v_mfma_f32_16x16x32_f16 v[48:51], v[124:127], v[164:167], v[48:51]
	v_mfma_f32_16x16x32_f16 v[36:39], v[116:119], v[192:195], v[36:39]
	v_mfma_f32_16x16x32_f16 v[32:35], v[124:127], v[192:195], v[32:35]
	v_mfma_f32_16x16x32_f16 v[20:23], v[116:119], v[206:209], v[20:23]
	v_mfma_f32_16x16x32_f16 v[16:19], v[124:127], v[206:209], v[16:19]
	v_mfma_f32_16x16x32_f16 v[4:7], v[116:119], v[214:217], v[4:7]
	v_mfma_f32_16x16x32_f16 v[0:3], v[124:127], v[214:217], v[0:3]
	v_mfma_f32_16x16x32_f16 v[60:63], v[144:147], v[160:163], v[60:63]
	v_mfma_f32_16x16x32_f16 v[56:59], v[152:155], v[160:163], v[56:59]
	v_mfma_f32_16x16x32_f16 v[44:47], v[144:147], v[168:171], v[44:47]
	v_mfma_f32_16x16x32_f16 v[40:43], v[152:155], v[168:171], v[40:43]
	v_mfma_f32_16x16x32_f16 v[28:31], v[144:147], v[202:205], v[28:31]
	v_mfma_f32_16x16x32_f16 v[24:27], v[152:155], v[202:205], v[24:27]
	v_mfma_f32_16x16x32_f16 v[12:15], v[144:147], v[210:213], v[12:15]
	v_mfma_f32_16x16x32_f16 v[8:11], v[152:155], v[210:213], v[8:11]
	v_mfma_f32_16x16x32_f16 v[60:63], v[148:151], v[164:167], v[60:63]
	v_mfma_f32_16x16x32_f16 v[56:59], v[156:159], v[164:167], v[56:59]
	v_mfma_f32_16x16x32_f16 v[44:47], v[148:151], v[192:195], v[44:47]
	v_mfma_f32_16x16x32_f16 v[40:43], v[156:159], v[192:195], v[40:43]
	v_mfma_f32_16x16x32_f16 v[28:31], v[148:151], v[206:209], v[28:31]
	v_mfma_f32_16x16x32_f16 v[24:27], v[156:159], v[206:209], v[24:27]
	v_mfma_f32_16x16x32_f16 v[12:15], v[148:151], v[214:217], v[12:15]
	v_mfma_f32_16x16x32_f16 v[8:11], v[156:159], v[214:217], v[8:11]
	s_barrier
	s_bitcmp1_b32 s101, 16
	s_cbranch_scc0 .Lpkb_t
	s_sub_u32 s101, s101, 1

; #define PG8_STAGE(bufoff, gbase, voff) do { _Pragma("unroll") for (int _i = 0; _i < 2; ++_i) \
;         __builtin_amdgcn_global_load_lds((const unsigned*)((const char*)(gbase) + (voff)[_i]), (PG8_LAS unsigned*)(lds + (bufoff) + ldsw + _i * 8192), 16, 0, 0); } while (0)
; #define PG8_LDA(dst, b, h) do { _Pragma("unroll") for (int m = 0; m < 4; ++m) _Pragma("unroll") for (int k = 0; k < 2; ++k) dst[m][k] = *(const PG8_LAS bf16x8*)(lds + PG8_SA(b, h) + aoff + m * 2048 + k * 1024); } while (0)
; #define PG8_LDB(dst, b, h) do { _Pragma("unroll") for (int n = 0; n < 2; ++n) _Pragma("unroll") for (int k = 0; k < 2; ++k) dst[n][k] = *(const PG8_LAS bf16x8*)(lds + PG8_SB(b, h) + boff + n * 2048 + k * 1024); } while (0)
; #define PG8_WAIT_V(n) asm volatile("s_waitcnt vmcnt(" #n ")" ::: "memory")
; #define PG8_WAIT_L(n) asm volatile("s_waitcnt lgkmcnt(" #n ")" ::: "memory")
; #define PG8_BAR __builtin_amdgcn_s_barrier()
; #define PG8_SCHED __builtin_amdgcn_sched_barrier(0)
;     ...
;         const bool has_next = S.next(ui + 1, nxt);
;         const char* nA = has_next ? (const char*)g.A + (size_t)nxt.pm * tstep : cA; const char* nB = has_next ? (const char*)g.Bt + (size_t)nxt.pn * tstep : cB;
;         for (int t = 0; t < nt; t += 2) {
;             const bool last = (t == nt - 2);
;             const char* a1 = cA + (size_t)(t + 1) * kstep;
;             const char* a2 = last ? nA : cA + (size_t)(t + 2) * kstep; const char* b2 = last ? nB : cB + (size_t)(t + 2) * kstep;
;             const char* a3 = a2 + kstep; const char* b3 = b2 + kstep;
;             PG8_LDB(B0, 0, 0); PG8_LDB(B1, 0, 1); PG8_SCHED; PG8_LDA(At, 0, 0); PG8_STAGE(PG8_SA(1, 1), a1 + hstep, voffA);
;             PG8_WAIT_V(8); PG8_WAIT_L(0); PG8_BAR; PG8_MMA(0, 0, At, B0); PG8_MMA(0, 1, At, B1); PG8_BAR; PG8_SCHED;
;             PG8_LDA(At, 0, 1); PG8_STAGE(PG8_SB(0, 0), b2, voffB); PG8_STAGE(PG8_SB(0, 1), b2 + hstepB, voffB); PG8_STAGE(PG8_SA(0, 0), a2, voffA);
;             PG8_WAIT_V(8); PG8_WAIT_L(0); PG8_BAR; PG8_MMA(1, 0, At, B0); PG8_MMA(1, 1, At, B1); PG8_BAR; PG8_SCHED;
;             PG8_LDB(B0, 1, 0); PG8_LDB(B1, 1, 1); PG8_SCHED; PG8_LDA(At, 1, 0); PG8_STAGE(PG8_SA(0, 1), a2 + hstep, voffA);
.LBB0_732:
	v_add_u32_e32 v158, s37, v152
	v_add_u32_e32 v174, s38, v152
	ds_read_b128 v[128:131], v158
	ds_read_b128 v[148:151], v158 offset:1024
	ds_read_b128 v[154:157], v158 offset:2048
	ds_read_b128 v[158:161], v158 offset:3072
	ds_read_b128 v[162:165], v174
	ds_read_b128 v[166:169], v174 offset:1024
	ds_read_b128 v[170:173], v174 offset:2048
	ds_read_b128 v[174:177], v174 offset:3072
	s_add_u32 s20, s22, 0xfffc0080
	s_addc_u32 s21, s23, -1
	s_cmp_eq_u32 s53, 12
	s_cselect_b32 s25, s13, s21
	s_cselect_b32 s24, s49, s20
	s_cselect_b32 s21, s11, s52
	s_cselect_b32 s20, s50, s51
	v_lshl_add_u64 v[210:211], s[22:23], 0, v[140:141]
	s_add_i32 m0, s19, 0xc000
	ds_read_b128 v[178:181], v153
	ds_read_b128 v[182:185], v153 offset:1024
	ds_read_b128 v[186:189], v153 offset:2048
	ds_read_b128 v[190:193], v153 offset:3072
	ds_read_b128 v[194:197], v153 offset:4096
	ds_read_b128 v[198:201], v153 offset:5120
	ds_read_b128 v[202:205], v153 offset:6144
	ds_read_b128 v[206:209], v153 offset:7168
	global_load_lds_dwordx4 v[210:211], off
	v_lshl_add_u64 v[210:211], s[22:23], 0, v[142:143]
	s_add_i32 m0, s19, 0xe000
	s_nop 0
	global_load_lds_dwordx4 v[210:211], off
	s_waitcnt vmcnt(8)
	s_waitcnt lgkmcnt(0)
	s_barrier
	s_waitcnt lgkmcnt(0)
	v_mfma_f32_16x16x32_bf16 v[112:115], v[128:131], v[178:181], v[112:115]
	v_mfma_f32_16x16x32_bf16 v[116:119], v[154:157], v[178:181], v[116:119]
	v_mfma_f32_16x16x32_bf16 v[108:111], v[128:131], v[186:189], v[108:111]
	v_mfma_f32_16x16x32_bf16 v[104:107], v[154:157], v[186:189], v[104:107]
	v_mfma_f32_16x16x32_bf16 v[92:95], v[128:131], v[194:197], v[92:95]
	v_mfma_f32_16x16x32_bf16 v[88:91], v[154:157], v[194:197], v[88:91]
	v_mfma_f32_16x16x32_bf16 v[76:79], v[128:131], v[202:205], v[76:79]
	v_mfma_f32_16x16x32_bf16 v[72:75], v[154:157], v[202:205], v[72:75]
	v_mfma_f32_16x16x32_bf16 v[112:115], v[148:151], v[182:185], v[112:115]
	v_mfma_f32_16x16x32_bf16 v[116:119], v[158:161], v[182:185], v[116:119]
	v_mfma_f32_16x16x32_bf16 v[108:111], v[148:151], v[190:193], v[108:111]
	v_mfma_f32_16x16x32_bf16 v[104:107], v[158:161], v[190:193], v[104:107]
	v_mfma_f32_16x16x32_bf16 v[92:95], v[148:151], v[198:201], v[92:95]
	v_mfma_f32_16x16x32_bf16 v[88:91], v[158:161], v[198:201], v[88:91]
	v_mfma_f32_16x16x32_bf16 v[76:79], v[148:151], v[206:209], v[76:79]
	v_mfma_f32_16x16x32_bf16 v[72:75], v[158:161], v[206:209], v[72:75]
	v_mfma_f32_16x16x32_bf16 v[120:123], v[162:165], v[178:181], v[120:123]
	v_mfma_f32_16x16x32_bf16 v[124:127], v[170:173], v[178:181], v[124:127]
	v_mfma_f32_16x16x32_bf16 v[100:103], v[162:165], v[186:189], v[100:103]
	v_mfma_f32_16x16x32_bf16 v[96:99], v[170:173], v[186:189], v[96:99]
	v_mfma_f32_16x16x32_bf16 v[84:87], v[162:165], v[194:197], v[84:87]
	v_mfma_f32_16x16x32_bf16 v[80:83], v[170:173], v[194:197], v[80:83]
	v_mfma_f32_16x16x32_bf16 v[68:71], v[162:165], v[202:205], v[68:71]
	v_mfma_f32_16x16x32_bf16 v[64:67], v[170:173], v[202:205], v[64:67]
	v_mfma_f32_16x16x32_bf16 v[120:123], v[166:169], v[182:185], v[120:123]
	v_mfma_f32_16x16x32_bf16 v[124:127], v[174:177], v[182:185], v[124:127]
	v_mfma_f32_16x16x32_bf16 v[100:103], v[166:169], v[190:193], v[100:103]
	v_mfma_f32_16x16x32_bf16 v[96:99], v[174:177], v[190:193], v[96:99]
	v_mfma_f32_16x16x32_bf16 v[84:87], v[166:169], v[198:201], v[84:87]
	v_mfma_f32_16x16x32_bf16 v[80:83], v[174:177], v[198:201], v[80:83]
	v_mfma_f32_16x16x32_bf16 v[68:71], v[166:169], v[206:209], v[68:71]
	v_mfma_f32_16x16x32_bf16 v[64:67], v[174:177], v[206:209], v[64:67]
	s_barrier
	s_add_i32 s54, s37, s26
	v_lshl_add_u64 v[210:211], s[20:21], 0, v[134:135]
	s_mov_b32 m0, s54
	ds_read_b128 v[178:181], v153 offset:16384
	ds_read_b128 v[182:185], v153 offset:17408
	ds_read_b128 v[186:189], v153 offset:18432
	ds_read_b128 v[190:193], v153 offset:19456
	ds_read_b128 v[194:197], v153 offset:20480
	ds_read_b128 v[198:201], v153 offset:21504
	ds_read_b128 v[202:205], v153 offset:22528
	ds_read_b128 v[206:209], v153 offset:23552
	global_load_lds_dwordx4 v[210:211], off
	s_add_i32 m0, s54, 0x2000
	s_add_u32 s54, s20, 0x40000
	v_lshl_add_u64 v[212:213], s[20:21], 0, v[132:133]
	s_addc_u32 s55, s21, 0
	s_add_i32 s56, s38, s26
	global_load_lds_dwordx4 v[212:213], off
	v_lshl_add_u64 v[214:215], s[54:55], 0, v[134:135]
	s_mov_b32 m0, s56
	v_lshl_add_u64 v[216:217], s[24:25], 0, v[132:133]
	global_load_lds_dwordx4 v[214:215], off
	v_lshl_add_u64 v[214:215], s[54:55], 0, v[132:133]
	s_add_i32 m0, s56, 0x2000
	s_nop 0
	global_load_lds_dwordx4 v[214:215], off
	v_lshl_add_u64 v[214:215], s[24:25], 0, v[134:135]
	s_mov_b32 m0, s19
	s_nop 0
	global_load_lds_dwordx4 v[214:215], off
	s_mov_b32 m0, s27
	s_nop 0
	global_load_lds_dwordx4 v[216:217], off
	s_waitcnt vmcnt(8)
	s_waitcnt lgkmcnt(0)
	s_barrier
; #define PG8_STAGE(bufoff, gbase, voff) do { _Pragma("unroll") for (int _i = 0; _i < 2; ++_i) \
;         __builtin_amdgcn_global_load_lds((const unsigned*)((const char*)(gbase) + (voff)[_i]), (PG8_LAS unsigned*)(lds + (bufoff) + ldsw + _i * 8192), 16, 0, 0); } while (0)
; #define PG8_LDA(dst, b, h) do { _Pragma("unroll") for (int m = 0; m < 4; ++m) _Pragma("unroll") for (int k = 0; k < 2; ++k) dst[m][k] = *(const PG8_LAS bf16x8*)(lds + PG8_SA(b, h) + aoff + m * 2048 + k * 1024); } while (0)
; #define PG8_WAIT_V(n) asm volatile("s_waitcnt vmcnt(" #n ")" ::: "memory")
; #define PG8_WAIT_L(n) asm volatile("s_waitcnt lgkmcnt(" #n ")" ::: "memory")
; #define PG8_BAR __builtin_amdgcn_s_barrier()
; #define PG8_SCHED __builtin_amdgcn_sched_barrier(0)
;     ...
;             PG8_WAIT_V(8); PG8_WAIT_L(0); PG8_BAR; PG8_MMA(0, 0, At, B0); PG8_MMA(0, 1, At, B1); PG8_BAR; PG8_SCHED;
;             PG8_LDA(At, 1, 1); PG8_STAGE(PG8_SB(1, 0), b3, voffB); PG8_STAGE(PG8_SB(1, 1), b3 + hstepB, voffB); PG8_STAGE(PG8_SA(1, 0), a3, voffA);
;             PG8_WAIT_V(8); PG8_WAIT_L(0); PG8_BAR; PG8_MMA(1, 0, At, B0); PG8_MMA(1, 1, At, B1); PG8_BAR; PG8_SCHED;
	s_waitcnt lgkmcnt(0)
	v_mfma_f32_16x16x32_bf16 v[60:63], v[128:131], v[178:181], v[60:63]
	v_mfma_f32_16x16x32_bf16 v[56:59], v[154:157], v[178:181], v[56:59]
	v_mfma_f32_16x16x32_bf16 v[44:47], v[128:131], v[186:189], v[44:47]
	v_mfma_f32_16x16x32_bf16 v[40:43], v[154:157], v[186:189], v[40:43]
	v_mfma_f32_16x16x32_bf16 v[28:31], v[128:131], v[194:197], v[28:31]
	v_mfma_f32_16x16x32_bf16 v[24:27], v[154:157], v[194:197], v[24:27]
	v_mfma_f32_16x16x32_bf16 v[12:15], v[128:131], v[202:205], v[12:15]
	v_mfma_f32_16x16x32_bf16 v[8:11], v[154:157], v[202:205], v[8:11]
	v_mfma_f32_16x16x32_bf16 v[60:63], v[148:151], v[182:185], v[60:63]
	v_mfma_f32_16x16x32_bf16 v[56:59], v[158:161], v[182:185], v[56:59]
	v_mfma_f32_16x16x32_bf16 v[44:47], v[148:151], v[190:193], v[44:47]
	v_mfma_f32_16x16x32_bf16 v[40:43], v[158:161], v[190:193], v[40:43]
	v_mfma_f32_16x16x32_bf16 v[28:31], v[148:151], v[198:201], v[28:31]
	v_mfma_f32_16x16x32_bf16 v[24:27], v[158:161], v[198:201], v[24:27]
	v_mfma_f32_16x16x32_bf16 v[12:15], v[148:151], v[206:209], v[12:15]
	v_mfma_f32_16x16x32_bf16 v[8:11], v[158:161], v[206:209], v[8:11]
	v_mfma_f32_16x16x32_bf16 v[52:55], v[162:165], v[178:181], v[52:55]
	v_mfma_f32_16x16x32_bf16 v[48:51], v[170:173], v[178:181], v[48:51]
	v_mfma_f32_16x16x32_bf16 v[36:39], v[162:165], v[186:189], v[36:39]
	v_mfma_f32_16x16x32_bf16 v[32:35], v[170:173], v[186:189], v[32:35]
	v_mfma_f32_16x16x32_bf16 v[20:23], v[162:165], v[194:197], v[20:23]
	v_mfma_f32_16x16x32_bf16 v[16:19], v[170:173], v[194:197], v[16:19]
	v_mfma_f32_16x16x32_bf16 v[0:3], v[162:165], v[202:205], v[0:3]
	v_mfma_f32_16x16x32_bf16 v[4:7], v[170:173], v[202:205], v[4:7]
	v_mfma_f32_16x16x32_bf16 v[52:55], v[166:169], v[182:185], v[52:55]
	v_mfma_f32_16x16x32_bf16 v[48:51], v[174:177], v[182:185], v[48:51]
	v_mfma_f32_16x16x32_bf16 v[36:39], v[166:169], v[190:193], v[36:39]
	v_mfma_f32_16x16x32_bf16 v[32:35], v[174:177], v[190:193], v[32:35]
	v_mfma_f32_16x16x32_bf16 v[20:23], v[166:169], v[198:201], v[20:23]
	v_mfma_f32_16x16x32_bf16 v[16:19], v[174:177], v[198:201], v[16:19]
	v_mfma_f32_16x16x32_bf16 v[0:3], v[166:169], v[206:209], v[0:3]
	v_mfma_f32_16x16x32_bf16 v[4:7], v[174:177], v[206:209], v[4:7]
	s_barrier
	s_add_i32 s54, 0, 0x18000
	s_add_i32 s55, 0, 0x1c000
	v_add_u32_e32 v158, s54, v152
	v_add_u32_e32 v174, s55, v152
	ds_read_b128 v[128:131], v158
	ds_read_b128 v[148:151], v158 offset:1024
	ds_read_b128 v[154:157], v158 offset:2048
	ds_read_b128 v[158:161], v158 offset:3072
	ds_read_b128 v[162:165], v174
	ds_read_b128 v[166:169], v174 offset:1024
	ds_read_b128 v[170:173], v174 offset:2048
	ds_read_b128 v[174:177], v174 offset:3072
	s_add_u32 s24, s24, 0x40000
	s_addc_u32 s25, s25, 0
	s_mov_b32 m0, s28
	v_lshl_add_u64 v[218:219], s[24:25], 0, v[134:135]
	ds_read_b128 v[178:181], v153 offset:32768
	ds_read_b128 v[182:185], v153 offset:33792
	ds_read_b128 v[186:189], v153 offset:34816
	ds_read_b128 v[190:193], v153 offset:35840
	ds_read_b128 v[194:197], v153 offset:36864
	ds_read_b128 v[198:201], v153 offset:37888
	ds_read_b128 v[202:205], v153 offset:38912
	ds_read_b128 v[206:209], v153 offset:39936
	global_load_lds_dwordx4 v[218:219], off
	v_lshl_add_u64 v[218:219], s[24:25], 0, v[132:133]
	s_mov_b32 m0, s29
	s_nop 0
	global_load_lds_dwordx4 v[218:219], off
	s_waitcnt vmcnt(8)
	s_waitcnt lgkmcnt(0)
	s_barrier
	s_waitcnt lgkmcnt(0)
	v_mfma_f32_16x16x32_bf16 v[112:115], v[128:131], v[178:181], v[112:115]
	v_mfma_f32_16x16x32_bf16 v[116:119], v[154:157], v[178:181], v[116:119]
	v_mfma_f32_16x16x32_bf16 v[108:111], v[128:131], v[186:189], v[108:111]
	v_mfma_f32_16x16x32_bf16 v[104:107], v[154:157], v[186:189], v[104:107]
	v_mfma_f32_16x16x32_bf16 v[92:95], v[128:131], v[194:197], v[92:95]
	v_mfma_f32_16x16x32_bf16 v[88:91], v[154:157], v[194:197], v[88:91]
	v_mfma_f32_16x16x32_bf16 v[76:79], v[128:131], v[202:205], v[76:79]
	v_mfma_f32_16x16x32_bf16 v[72:75], v[154:157], v[202:205], v[72:75]
	v_mfma_f32_16x16x32_bf16 v[112:115], v[148:151], v[182:185], v[112:115]
	v_mfma_f32_16x16x32_bf16 v[116:119], v[158:161], v[182:185], v[116:119]
	v_mfma_f32_16x16x32_bf16 v[108:111], v[148:151], v[190:193], v[108:111]
	v_mfma_f32_16x16x32_bf16 v[104:107], v[158:161], v[190:193], v[104:107]
	v_mfma_f32_16x16x32_bf16 v[92:95], v[148:151], v[198:201], v[92:95]
	v_mfma_f32_16x16x32_bf16 v[88:91], v[158:161], v[198:201], v[88:91]
	v_mfma_f32_16x16x32_bf16 v[76:79], v[148:151], v[206:209], v[76:79]
	v_mfma_f32_16x16x32_bf16 v[72:75], v[158:161], v[206:209], v[72:75]
	v_mfma_f32_16x16x32_bf16 v[120:123], v[162:165], v[178:181], v[120:123]
	v_mfma_f32_16x16x32_bf16 v[124:127], v[170:173], v[178:181], v[124:127]
	v_mfma_f32_16x16x32_bf16 v[100:103], v[162:165], v[186:189], v[100:103]
	v_mfma_f32_16x16x32_bf16 v[96:99], v[170:173], v[186:189], v[96:99]
	v_mfma_f32_16x16x32_bf16 v[84:87], v[162:165], v[194:197], v[84:87]
	v_mfma_f32_16x16x32_bf16 v[80:83], v[170:173], v[194:197], v[80:83]
	v_mfma_f32_16x16x32_bf16 v[68:71], v[162:165], v[202:205], v[68:71]
	v_mfma_f32_16x16x32_bf16 v[64:67], v[170:173], v[202:205], v[64:67]
	v_mfma_f32_16x16x32_bf16 v[120:123], v[166:169], v[182:185], v[120:123]
	v_mfma_f32_16x16x32_bf16 v[124:127], v[174:177], v[182:185], v[124:127]
	v_mfma_f32_16x16x32_bf16 v[100:103], v[166:169], v[190:193], v[100:103]
	v_mfma_f32_16x16x32_bf16 v[96:99], v[174:177], v[190:193], v[96:99]
	v_mfma_f32_16x16x32_bf16 v[84:87], v[166:169], v[198:201], v[84:87]
	v_mfma_f32_16x16x32_bf16 v[80:83], v[174:177], v[198:201], v[80:83]
	v_mfma_f32_16x16x32_bf16 v[68:71], v[166:169], v[206:209], v[68:71]
	v_mfma_f32_16x16x32_bf16 v[64:67], v[174:177], v[206:209], v[64:67]
	s_barrier
; #define PG8_STAGE(bufoff, gbase, voff) do { _Pragma("unroll") for (int _i = 0; _i < 2; ++_i) \
;         __builtin_amdgcn_global_load_lds((const unsigned*)((const char*)(gbase) + (voff)[_i]), (PG8_LAS unsigned*)(lds + (bufoff) + ldsw + _i * 8192), 16, 0, 0); } while (0)
; #define PG8_LDA(dst, b, h) do { _Pragma("unroll") for (int m = 0; m < 4; ++m) _Pragma("unroll") for (int k = 0; k < 2; ++k) dst[m][k] = *(const PG8_LAS bf16x8*)(lds + PG8_SA(b, h) + aoff + m * 2048 + k * 1024); } while (0)
; #define PG8_WAIT_V(n) asm volatile("s_waitcnt vmcnt(" #n ")" ::: "memory")
; #define PG8_WAIT_L(n) asm volatile("s_waitcnt lgkmcnt(" #n ")" ::: "memory")
; #define PG8_BAR __builtin_amdgcn_s_barrier()
; #define PG8_SCHED __builtin_amdgcn_sched_barrier(0)
;     ...
;             PG8_LDA(At, 1, 1); PG8_STAGE(PG8_SB(1, 0), b3, voffB); PG8_STAGE(PG8_SB(1, 1), b3 + hstepB, voffB); PG8_STAGE(PG8_SA(1, 0), a3, voffA);
;             PG8_WAIT_V(8); PG8_WAIT_L(0); PG8_BAR; PG8_MMA(1, 0, At, B0); PG8_MMA(1, 1, At, B1); PG8_BAR; PG8_SCHED;
;         }
	s_add_i32 s24, s54, s26
	v_lshl_add_u64 v[210:211], v[210:211], 0, s[6:7]
	s_mov_b32 m0, s24
	ds_read_b128 v[178:181], v153 offset:49152
	ds_read_b128 v[182:185], v153 offset:50176
	ds_read_b128 v[186:189], v153 offset:51200
	ds_read_b128 v[190:193], v153 offset:52224
	ds_read_b128 v[194:197], v153 offset:53248
	ds_read_b128 v[198:201], v153 offset:54272
	ds_read_b128 v[202:205], v153 offset:55296
	ds_read_b128 v[206:209], v153 offset:56320
	global_load_lds_dwordx4 v[210:211], off
	s_add_i32 m0, s24, 0x2000
	s_add_u32 s20, s20, 0x40080
	v_lshl_add_u64 v[210:211], v[212:213], 0, s[6:7]
	s_addc_u32 s21, s21, 0
	s_add_i32 s24, s55, s26
	global_load_lds_dwordx4 v[210:211], off
	v_lshl_add_u64 v[210:211], s[20:21], 0, v[134:135]
	s_mov_b32 m0, s24
	s_nop 0
	global_load_lds_dwordx4 v[210:211], off
	v_lshl_add_u64 v[210:211], s[20:21], 0, v[132:133]
	s_add_i32 m0, s24, 0x2000
	s_nop 0
	global_load_lds_dwordx4 v[210:211], off
	v_lshl_add_u64 v[210:211], v[214:215], 0, s[6:7]
	s_mov_b32 m0, s33
	s_nop 0
	global_load_lds_dwordx4 v[210:211], off
	v_lshl_add_u64 v[210:211], v[216:217], 0, s[6:7]
	s_mov_b32 m0, s34
	s_nop 0
	global_load_lds_dwordx4 v[210:211], off
	s_waitcnt vmcnt(8)
	s_waitcnt lgkmcnt(0)
	s_barrier
	s_waitcnt lgkmcnt(0)
	v_mfma_f32_16x16x32_bf16 v[60:63], v[128:131], v[178:181], v[60:63]
	v_mfma_f32_16x16x32_bf16 v[56:59], v[154:157], v[178:181], v[56:59]
	v_mfma_f32_16x16x32_bf16 v[44:47], v[128:131], v[186:189], v[44:47]
	v_mfma_f32_16x16x32_bf16 v[40:43], v[154:157], v[186:189], v[40:43]
	v_mfma_f32_16x16x32_bf16 v[28:31], v[128:131], v[194:197], v[28:31]
	v_mfma_f32_16x16x32_bf16 v[24:27], v[154:157], v[194:197], v[24:27]
	v_mfma_f32_16x16x32_bf16 v[12:15], v[128:131], v[202:205], v[12:15]
	v_mfma_f32_16x16x32_bf16 v[8:11], v[154:157], v[202:205], v[8:11]
	v_mfma_f32_16x16x32_bf16 v[60:63], v[148:151], v[182:185], v[60:63]
	v_mfma_f32_16x16x32_bf16 v[56:59], v[158:161], v[182:185], v[56:59]
	v_mfma_f32_16x16x32_bf16 v[44:47], v[148:151], v[190:193], v[44:47]
	v_mfma_f32_16x16x32_bf16 v[40:43], v[158:161], v[190:193], v[40:43]
	v_mfma_f32_16x16x32_bf16 v[28:31], v[148:151], v[198:201], v[28:31]
	v_mfma_f32_16x16x32_bf16 v[24:27], v[158:161], v[198:201], v[24:27]
	v_mfma_f32_16x16x32_bf16 v[12:15], v[148:151], v[206:209], v[12:15]
	v_mfma_f32_16x16x32_bf16 v[8:11], v[158:161], v[206:209], v[8:11]
	v_mfma_f32_16x16x32_bf16 v[52:55], v[162:165], v[178:181], v[52:55]
	v_mfma_f32_16x16x32_bf16 v[48:51], v[170:173], v[178:181], v[48:51]
	v_mfma_f32_16x16x32_bf16 v[36:39], v[162:165], v[186:189], v[36:39]
	v_mfma_f32_16x16x32_bf16 v[32:35], v[170:173], v[186:189], v[32:35]
	v_mfma_f32_16x16x32_bf16 v[20:23], v[162:165], v[194:197], v[20:23]
	v_mfma_f32_16x16x32_bf16 v[16:19], v[170:173], v[194:197], v[16:19]
	v_mfma_f32_16x16x32_bf16 v[0:3], v[162:165], v[202:205], v[0:3]
	v_mfma_f32_16x16x32_bf16 v[4:7], v[170:173], v[202:205], v[4:7]
	v_mfma_f32_16x16x32_bf16 v[52:55], v[166:169], v[182:185], v[52:55]
	v_mfma_f32_16x16x32_bf16 v[48:51], v[174:177], v[182:185], v[48:51]
	v_mfma_f32_16x16x32_bf16 v[36:39], v[166:169], v[190:193], v[36:39]
	v_mfma_f32_16x16x32_bf16 v[32:35], v[174:177], v[190:193], v[32:35]
	v_mfma_f32_16x16x32_bf16 v[20:23], v[166:169], v[198:201], v[20:23]
	v_mfma_f32_16x16x32_bf16 v[16:19], v[174:177], v[198:201], v[16:19]
	v_mfma_f32_16x16x32_bf16 v[0:3], v[166:169], v[206:209], v[0:3]
	v_mfma_f32_16x16x32_bf16 v[4:7], v[174:177], v[206:209], v[4:7]
	s_barrier
	s_add_i32 s53, s53, 2
	s_add_u32 s22, s22, 0x100
	s_addc_u32 s23, s23, 0
	s_add_u32 s51, s51, 0x100
	s_addc_u32 s52, s52, 0
	s_cmp_gt_u32 s53, 13
	s_cbranch_scc0 .LBB0_732
	s_and_b64 vcc, exec, s[8:9]
	s_cbranch_vccz .LBB0_735
	s_barrier
